# MLA loop v2 (lazy running max with biased QK accumulators, less VALU) + 3 GEMM K-loops with pipelined LDS fragment reads and scalar m0 stepping
# speedup vs baseline: 1.0542x; 1.0309x over previous
.LBB0_193:
	s_add_i32 s2, s92, s85
	s_cmpk_gt_i32 s2, 0x167f
	s_cbranch_scc1 .LBB0_192
	s_ashr_i32 s3, s2, 5
	s_mul_hi_i32 s4, s3, 0x66666667
	s_lshr_b32 s5, s4, 31
	s_ashr_i32 s4, s4, 1
	s_add_i32 s5, s4, s5
	s_lshl_b32 s4, s5, 3
	s_bfe_u32 s8, s2, 0x30002
	s_or_b32 s4, s4, s8
	s_mul_i32 s5, s5, 5
	s_sub_i32 s3, s3, s5
	s_lshl_b32 s24, s4, 7
	s_lshl_b32 s3, s3, 2
	s_and_b32 s2, s2, 3
	s_ashr_i32 s25, s24, 31
	s_or_b32 s26, s3, s2
	s_lshl_b64 s[2:3], s[24:25], 11
	s_add_u32 s2, s64, s2
	s_addc_u32 s3, s86, s3
	s_ashr_i32 s27, s26, 31
	v_mov_b32_e32 v4, v111
	s_lshl_b64 s[8:9], s[26:27], 18
	s_add_u32 s8, s93, s8
	v_ashrrev_i32_e32 v0, 3, v4
	v_lshrrev_b32_e32 v6, 4, v4
	v_xor_b32_e32 v8, v6, v4
	v_ashrrev_i32_e32 v1, 31, v0
	s_addc_u32 s9, s20, s9
	v_lshlrev_b64 v[0:1], 11, v[0:1]
	v_lshlrev_b32_e32 v8, 4, v8
	v_lshl_add_u64 v[2:3], s[2:3], 0, v[0:1]
	v_and_b32_e32 v108, 0x70, v8
	v_lshl_add_u64 v[0:1], s[8:9], 0, v[0:1]
	s_waitcnt vmcnt(11)
	v_lshlrev_b32_e32 v83, 4, v4
	v_lshl_add_u64 v[66:67], v[0:1], 0, v[108:109]
	v_readfirstlane_b32 s2, v83
	v_add_u32_e32 v0, 0x1000, v83
	v_lshl_add_u64 v[64:65], v[2:3], 0, v[108:109]
	s_mov_b32 m0, s2
	s_mov_b64 s[8:9], 0x10000
	v_readfirstlane_b32 s2, v0
	v_add_u32_e32 v0, 0x2000, v83
	global_load_lds_dwordx4 v[64:65], off
	v_lshl_add_u64 v[68:69], v[64:65], 0, s[8:9]
	s_mov_b32 m0, s2
	s_mov_b64 s[16:17], 0x20000
	v_readfirstlane_b32 s2, v0
	v_add_u32_e32 v0, 0x3000, v83
	global_load_lds_dwordx4 v[68:69], off
	v_lshl_add_u64 v[70:71], v[64:65], 0, s[16:17]
	s_mov_b32 m0, s2
	s_mov_b64 s[28:29], 0x30000
	v_readfirstlane_b32 s2, v0
	v_add_u32_e32 v0, 0x4000, v83
	global_load_lds_dwordx4 v[70:71], off
	v_lshl_add_u64 v[72:73], v[64:65], 0, s[28:29]
	s_mov_b32 m0, s2
	v_readfirstlane_b32 s2, v0
	v_add_u32_e32 v0, 0x5000, v83
	global_load_lds_dwordx4 v[72:73], off
	s_mov_b32 m0, s2
	v_readfirstlane_b32 s2, v0
	v_add_u32_e32 v0, 0x6000, v83
	global_load_lds_dwordx4 v[66:67], off
	v_lshl_add_u64 v[74:75], v[66:67], 0, s[8:9]
	s_mov_b32 m0, s2
	v_readfirstlane_b32 s2, v0
	v_add_u32_e32 v0, 0x7000, v83
	global_load_lds_dwordx4 v[74:75], off
	v_lshl_add_u64 v[76:77], v[66:67], 0, s[16:17]
	s_mov_b32 m0, s2
	v_readfirstlane_b32 s2, v0
	global_load_lds_dwordx4 v[76:77], off
	v_lshl_add_u64 v[78:79], v[66:67], 0, s[28:29]
	s_mov_b32 m0, s2
	v_and_b32_e32 v5, 15, v4
	global_load_lds_dwordx4 v[78:79], off
	v_lshrrev_b32_e32 v0, 1, v4
	v_and_or_b32 v0, v0, s84, v5
	v_lshlrev_b32_e32 v81, 7, v0
	v_lshlrev_b32_e32 v0, 7, v4
	v_bfe_u32 v7, v4, 4, 2
	v_and_b32_e32 v80, 0x2780, v0
	v_bfe_u32 v0, v4, 1, 3
	v_bitop3_b32 v1, v6, v0, 3 bitop3:0x6c
	v_bitop3_b32 v0, v7, v0, 4 bitop3:0x36
	v_lshlrev_b32_e32 v82, 4, v0
	v_mov_b32_e32 v0, 0
	s_waitcnt vmcnt(0)
	v_lshlrev_b32_e32 v84, 4, v1
	s_mov_b32 s3, 0
	s_mov_b32 s2, 0x8000
	v_mov_b32_e32 v1, v0
	v_mov_b32_e32 v2, v0
	v_mov_b32_e32 v3, v0
	v_mov_b32_e32 v4, v0
	v_mov_b32_e32 v5, v0
	v_mov_b32_e32 v6, v0
	v_mov_b32_e32 v7, v0
	v_mov_b32_e32 v8, v0
	v_mov_b32_e32 v9, v0
	v_mov_b32_e32 v10, v0
	v_mov_b32_e32 v11, v0
	v_mov_b32_e32 v12, v0
	v_mov_b32_e32 v13, v0
	v_mov_b32_e32 v14, v0
	v_mov_b32_e32 v15, v0
	v_mov_b32_e32 v16, v0
	v_mov_b32_e32 v17, v0
	v_mov_b32_e32 v18, v0
	v_mov_b32_e32 v19, v0
	v_mov_b32_e32 v20, v0
	v_mov_b32_e32 v21, v0
	v_mov_b32_e32 v22, v0
	v_mov_b32_e32 v23, v0
	v_mov_b32_e32 v24, v0
	v_mov_b32_e32 v25, v0
	v_mov_b32_e32 v26, v0
	v_mov_b32_e32 v27, v0
	v_mov_b32_e32 v28, v0
	v_mov_b32_e32 v29, v0
	v_mov_b32_e32 v30, v0
	v_mov_b32_e32 v31, v0
	v_mov_b32_e32 v32, v0
	v_mov_b32_e32 v33, v0
	v_mov_b32_e32 v34, v0
	v_mov_b32_e32 v35, v0
	v_mov_b32_e32 v36, v0
	v_mov_b32_e32 v37, v0
	v_mov_b32_e32 v38, v0
	v_mov_b32_e32 v39, v0
	v_mov_b32_e32 v40, v0
	v_mov_b32_e32 v41, v0
	v_mov_b32_e32 v42, v0
	v_mov_b32_e32 v43, v0
	v_mov_b32_e32 v44, v0
	v_mov_b32_e32 v45, v0
	v_mov_b32_e32 v46, v0
	v_mov_b32_e32 v47, v0
	v_mov_b32_e32 v48, v0
	v_mov_b32_e32 v49, v0
	v_mov_b32_e32 v50, v0
	v_mov_b32_e32 v51, v0
	v_mov_b32_e32 v52, v0
	v_mov_b32_e32 v53, v0
	v_mov_b32_e32 v54, v0
	v_mov_b32_e32 v55, v0
	v_mov_b32_e32 v56, v0
	v_mov_b32_e32 v57, v0
	v_mov_b32_e32 v58, v0
	v_mov_b32_e32 v59, v0
	v_mov_b32_e32 v60, v0
	v_mov_b32_e32 v61, v0
	v_mov_b32_e32 v62, v0
	v_mov_b32_e32 v63, v0
	s_waitcnt vmcnt(0) lgkmcnt(0)
	s_barrier
	v_readfirstlane_b32 s16, v83
	s_mov_b64 s[98:99], 0x80
	v_lshl_add_u64 v[64:65], v[64:65], 0, s[98:99]
	v_lshl_add_u64 v[68:69], v[68:69], 0, s[98:99]
	v_lshl_add_u64 v[70:71], v[70:71], 0, s[98:99]
	v_lshl_add_u64 v[72:73], v[72:73], 0, s[98:99]
	v_lshl_add_u64 v[66:67], v[66:67], 0, s[98:99]
	v_lshl_add_u64 v[74:75], v[74:75], 0, s[98:99]
	v_lshl_add_u64 v[76:77], v[76:77], 0, s[98:99]
	v_lshl_add_u64 v[78:79], v[78:79], 0, s[98:99]
.LBB0_195:
	s_add_i32 s5, s2, 0xffff8000
	s_and_b32 s5, s5, 0x8000
	s_xor_b32 s3, s5, 0x8000
	s_add_u32 s3, s3, s16
	s_mov_b32 s8, s3
	s_mov_b32 m0, s8
	s_add_u32 s8, s3, 0x1000
	v_add_u32_e32 v85, s5, v81
	global_load_lds_dwordx4 v[64:65], off
	v_lshl_add_u64 v[64:65], v[64:65], 0, s[98:99]
	s_mov_b32 m0, s8
	s_add_u32 s8, s3, 0x2000
	v_or_b32_e32 v106, s5, v80
	global_load_lds_dwordx4 v[68:69], off
	v_lshl_add_u64 v[68:69], v[68:69], 0, s[98:99]
	s_mov_b32 m0, s8
	s_add_u32 s8, s3, 0x3000
	v_add_u32_e32 v250, v85, v84
	global_load_lds_dwordx4 v[70:71], off
	v_lshl_add_u64 v[70:71], v[70:71], 0, s[98:99]
	s_mov_b32 m0, s8
	s_add_u32 s8, s3, 0x4000
	v_add_u32_e32 v251, v106, v84
	global_load_lds_dwordx4 v[72:73], off
	v_lshl_add_u64 v[72:73], v[72:73], 0, s[98:99]
	s_mov_b32 m0, s8
	s_add_u32 s8, s3, 0x5000
	v_add_u32_e32 v252, v85, v82
	global_load_lds_dwordx4 v[66:67], off
	v_lshl_add_u64 v[66:67], v[66:67], 0, s[98:99]
	s_mov_b32 m0, s8
	s_add_u32 s8, s3, 0x6000
	v_add_u32_e32 v253, v106, v82
	global_load_lds_dwordx4 v[74:75], off
	v_lshl_add_u64 v[74:75], v[74:75], 0, s[98:99]
	s_mov_b32 m0, s8
	s_add_u32 s8, s3, 0x7000
	s_nop 0
	global_load_lds_dwordx4 v[76:77], off
	v_lshl_add_u64 v[76:77], v[76:77], 0, s[98:99]
	s_mov_b32 m0, s8
	s_add_u32 s8, s3, 0x8000
	s_nop 0
	global_load_lds_dwordx4 v[78:79], off
	v_lshl_add_u64 v[78:79], v[78:79], 0, s[98:99]
	ds_read_b128 v[86:89], v250
	ds_read_b128 v[102:105], v251 offset:16384
	ds_read_b128 v[122:125], v251 offset:18432
	ds_read_b128 v[126:129], v251 offset:20480
	ds_read_b128 v[130:133], v251 offset:22528
	ds_read_b128 v[90:93], v250 offset:2048
	ds_read_b128 v[94:97], v250 offset:4096
	ds_read_b128 v[98:101], v250 offset:6144
	ds_read_b128 v[218:221], v252
	ds_read_b128 v[234:237], v253 offset:16384
	ds_read_b128 v[238:241], v253 offset:18432
	ds_read_b128 v[242:245], v253 offset:20480
	ds_read_b128 v[246:249], v253 offset:22528
	ds_read_b128 v[222:225], v252 offset:2048
	ds_read_b128 v[226:229], v252 offset:4096
	s_waitcnt lgkmcnt(13)
	v_mfma_f32_16x16x32_bf16 v[60:63], v[86:89], v[102:105], v[60:63]
	ds_read_b128 v[230:233], v252 offset:6144
	s_waitcnt lgkmcnt(13)
	v_mfma_f32_16x16x32_bf16 v[56:59], v[86:89], v[122:125], v[56:59]
	s_waitcnt lgkmcnt(12)
	v_mfma_f32_16x16x32_bf16 v[52:55], v[86:89], v[126:129], v[52:55]
	s_waitcnt lgkmcnt(11)
	v_mfma_f32_16x16x32_bf16 v[48:51], v[86:89], v[130:133], v[48:51]
	s_waitcnt lgkmcnt(10)
	v_mfma_f32_16x16x32_bf16 v[44:47], v[90:93], v[102:105], v[44:47]
	v_mfma_f32_16x16x32_bf16 v[40:43], v[90:93], v[122:125], v[40:43]
	v_mfma_f32_16x16x32_bf16 v[36:39], v[90:93], v[126:129], v[36:39]
	v_mfma_f32_16x16x32_bf16 v[32:35], v[90:93], v[130:133], v[32:35]
	s_waitcnt lgkmcnt(9)
	v_mfma_f32_16x16x32_bf16 v[28:31], v[94:97], v[102:105], v[28:31]
	v_mfma_f32_16x16x32_bf16 v[24:27], v[94:97], v[122:125], v[24:27]
	v_mfma_f32_16x16x32_bf16 v[20:23], v[94:97], v[126:129], v[20:23]
	v_mfma_f32_16x16x32_bf16 v[16:19], v[94:97], v[130:133], v[16:19]
	s_waitcnt lgkmcnt(8)
	v_mfma_f32_16x16x32_bf16 v[12:15], v[98:101], v[102:105], v[12:15]
	v_mfma_f32_16x16x32_bf16 v[8:11], v[98:101], v[122:125], v[8:11]
	v_mfma_f32_16x16x32_bf16 v[4:7], v[98:101], v[126:129], v[4:7]
	v_mfma_f32_16x16x32_bf16 v[0:3], v[98:101], v[130:133], v[0:3]
	s_waitcnt lgkmcnt(6)
	v_mfma_f32_16x16x32_bf16 v[60:63], v[218:221], v[234:237], v[60:63]
	s_waitcnt lgkmcnt(5)
	v_mfma_f32_16x16x32_bf16 v[56:59], v[218:221], v[238:241], v[56:59]
	s_waitcnt lgkmcnt(4)
	v_mfma_f32_16x16x32_bf16 v[52:55], v[218:221], v[242:245], v[52:55]
	s_waitcnt lgkmcnt(3)
	v_mfma_f32_16x16x32_bf16 v[48:51], v[218:221], v[246:249], v[48:51]
	s_waitcnt lgkmcnt(2)
	v_mfma_f32_16x16x32_bf16 v[44:47], v[222:225], v[234:237], v[44:47]
	v_mfma_f32_16x16x32_bf16 v[40:43], v[222:225], v[238:241], v[40:43]
	v_mfma_f32_16x16x32_bf16 v[36:39], v[222:225], v[242:245], v[36:39]
	v_mfma_f32_16x16x32_bf16 v[32:35], v[222:225], v[246:249], v[32:35]
	s_waitcnt lgkmcnt(1)
	v_mfma_f32_16x16x32_bf16 v[28:31], v[226:229], v[234:237], v[28:31]
	v_mfma_f32_16x16x32_bf16 v[24:27], v[226:229], v[238:241], v[24:27]
	v_mfma_f32_16x16x32_bf16 v[20:23], v[226:229], v[242:245], v[20:23]
	v_mfma_f32_16x16x32_bf16 v[16:19], v[226:229], v[246:249], v[16:19]
	s_waitcnt lgkmcnt(0)
	v_mfma_f32_16x16x32_bf16 v[12:15], v[230:233], v[234:237], v[12:15]
	v_mfma_f32_16x16x32_bf16 v[8:11], v[230:233], v[238:241], v[8:11]
	v_mfma_f32_16x16x32_bf16 v[4:7], v[230:233], v[242:245], v[4:7]
	v_mfma_f32_16x16x32_bf16 v[0:3], v[230:233], v[246:249], v[0:3]
	s_add_i32 s2, s2, 0x8000
	s_cmp_lg_u32 s2, 0x80000
	s_waitcnt vmcnt(0)
	s_barrier
	s_cbranch_scc1 .LBB0_195
	v_add_u32_e32 v83, v81, v84
	ds_read_b128 v[64:67], v83 offset:32768
	v_add_u32_e32 v84, v80, v84
	ds_read_b128 v[68:71], v84 offset:49152
	ds_read_b128 v[72:75], v84 offset:51200
	ds_read_b128 v[76:79], v84 offset:53248
	ds_read_b128 v[84:87], v84 offset:55296
	v_add_u32_e32 v88, v81, v82
	v_add_u32_e32 v80, v80, v82
	s_waitcnt lgkmcnt(3)
	v_mfma_f32_16x16x32_bf16 v[60:63], v[64:67], v[68:71], v[60:63]
	s_waitcnt lgkmcnt(2)
	v_mfma_f32_16x16x32_bf16 v[56:59], v[64:67], v[72:75], v[56:59]
	s_waitcnt lgkmcnt(1)
	v_mfma_f32_16x16x32_bf16 v[52:55], v[64:67], v[76:79], v[52:55]
	s_waitcnt lgkmcnt(0)
	v_mfma_f32_16x16x32_bf16 v[48:51], v[64:67], v[84:87], v[48:51]
	ds_read_b128 v[64:67], v83 offset:34816
	s_waitcnt lgkmcnt(0)
	v_mfma_f32_16x16x32_bf16 v[44:47], v[64:67], v[68:71], v[44:47]
	v_mfma_f32_16x16x32_bf16 v[40:43], v[64:67], v[72:75], v[40:43]
	v_mfma_f32_16x16x32_bf16 v[36:39], v[64:67], v[76:79], v[36:39]
	v_mfma_f32_16x16x32_bf16 v[32:35], v[64:67], v[84:87], v[32:35]
	ds_read_b128 v[64:67], v83 offset:36864
	s_waitcnt lgkmcnt(0)
	v_mfma_f32_16x16x32_bf16 v[28:31], v[64:67], v[68:71], v[28:31]
	v_mfma_f32_16x16x32_bf16 v[24:27], v[64:67], v[72:75], v[24:27]
	v_mfma_f32_16x16x32_bf16 v[20:23], v[64:67], v[76:79], v[20:23]
	v_mfma_f32_16x16x32_bf16 v[16:19], v[64:67], v[84:87], v[16:19]
	ds_read_b128 v[64:67], v83 offset:38912
	s_waitcnt lgkmcnt(0)
	v_mfma_f32_16x16x32_bf16 v[12:15], v[64:67], v[68:71], v[12:15]
	ds_read_b128 v[68:71], v88 offset:32768
	v_mfma_f32_16x16x32_bf16 v[8:11], v[64:67], v[72:75], v[8:11]
	ds_read_b128 v[72:75], v80 offset:51200
	v_mfma_f32_16x16x32_bf16 v[4:7], v[64:67], v[76:79], v[4:7]
	ds_read_b128 v[76:79], v80 offset:53248
	v_mfma_f32_16x16x32_bf16 v[0:3], v[64:67], v[84:87], v[0:3]
	ds_read_b128 v[64:67], v80 offset:49152
	ds_read_b128 v[80:83], v80 offset:55296
	s_waitcnt lgkmcnt(1)
	v_mfma_f32_16x16x32_bf16 v[60:63], v[68:71], v[64:67], v[60:63]
	v_mfma_f32_16x16x32_bf16 v[56:59], v[68:71], v[72:75], v[56:59]
	v_mfma_f32_16x16x32_bf16 v[52:55], v[68:71], v[76:79], v[52:55]
	s_waitcnt lgkmcnt(0)
	v_mfma_f32_16x16x32_bf16 v[48:51], v[68:71], v[80:83], v[48:51]
	ds_read_b128 v[68:71], v88 offset:34816
	s_waitcnt lgkmcnt(0)
	v_mfma_f32_16x16x32_bf16 v[44:47], v[68:71], v[64:67], v[44:47]
	v_mfma_f32_16x16x32_bf16 v[40:43], v[68:71], v[72:75], v[40:43]
	v_mfma_f32_16x16x32_bf16 v[36:39], v[68:71], v[76:79], v[36:39]
	v_mfma_f32_16x16x32_bf16 v[32:35], v[68:71], v[80:83], v[32:35]
	ds_read_b128 v[68:71], v88 offset:36864
	s_waitcnt lgkmcnt(0)
	v_mfma_f32_16x16x32_bf16 v[28:31], v[68:71], v[64:67], v[28:31]
	v_mfma_f32_16x16x32_bf16 v[24:27], v[68:71], v[72:75], v[24:27]
	v_mfma_f32_16x16x32_bf16 v[20:23], v[68:71], v[76:79], v[20:23]
	v_mfma_f32_16x16x32_bf16 v[16:19], v[68:71], v[80:83], v[16:19]
	ds_read_b128 v[68:71], v88 offset:38912
	s_waitcnt lgkmcnt(0)
	v_mfma_f32_16x16x32_bf16 v[12:15], v[68:71], v[64:67], v[12:15]
	v_mfma_f32_16x16x32_bf16 v[8:11], v[68:71], v[72:75], v[8:11]
	v_mfma_f32_16x16x32_bf16 v[4:7], v[68:71], v[76:79], v[4:7]
	v_mfma_f32_16x16x32_bf16 v[0:3], v[68:71], v[80:83], v[0:3]
	v_mov_b32_e32 v88, v111
	s_barrier
	s_cmp_gt_i32 s26, 12
	v_ashrrev_i32_e32 v86, 7, v88
	v_bfe_u32 v85, v88, 6, 1
	v_and_b32_e32 v84, 15, v88
	v_bfe_u32 v87, v88, 4, 2
	s_mov_b64 s[2:3], -1
	s_cbranch_scc0 .LBB0_398
	s_add_i32 s2, s24, 0xfffff000
	s_ashr_i32 s8, s4, 1
	s_cmp_lt_i32 s4, 32
	s_cselect_b64 s[28:29], -1, 0
	s_lshr_b32 s9, s2, 12
	s_cmp_gt_i32 s4, 31
	s_cselect_b64 s[2:3], -1, 0
	s_and_b64 s[4:5], s[2:3], exec
	s_movk_i32 s4, 0xf80
	s_cselect_b32 s4, s4, 0x80
	s_cselect_b32 s30, s9, s8
	s_and_b32 s25, s4, s24
	s_cmp_lg_u32 s26, 13
	s_mov_b64 s[4:5], -1
	s_cbranch_scc0 .LBB0_330
	s_cmp_gt_u32 s26, 18
	s_cbranch_scc0 .LBB0_232
	s_and_b64 s[4:5], s[2:3], exec
	s_mov_b32 s4, 0x105dc000
	s_cselect_b32 s4, s4, 0x10ddc000
	s_add_u32 s16, s60, s4
	s_addc_u32 s17, s62, 0
	s_ashr_i32 s31, s30, 31
	s_lshl_b64 s[4:5], s[30:31], 7
	v_lshl_add_u32 v64, v86, 6, s25
	s_and_b64 s[2:3], s[2:3], exec
	v_lshl_or_b32 v64, v87, 2, v64
	v_lshlrev_b32_e32 v76, 6, v85
	s_cselect_b32 s8, 12, 8
	s_lshl_b64 s[2:3], s[30:31], 10
	v_or_b32_e32 v89, s4, v76
	s_add_u32 s4, s2, s6
	v_ashrrev_i32_e32 v65, 31, v64
	v_mov_b32_e32 v73, s5
	s_addc_u32 s5, s3, s7
	v_lshl_add_u64 v[80:81], v[64:65], 1, s[16:17]
	v_lshl_add_u64 v[68:69], s[4:5], 0, v[64:65]
	v_or_b32_e32 v72, v89, v84
	v_lshlrev_b64 v[66:67], s8, v[72:73]
	v_cndmask_b32_e64 v65, 0, 1, s[28:29]
	v_lshlrev_b64 v[74:75], 9, v[68:69]
	v_cvt_pk_bf16_f32 v70, v60, v61
	v_cvt_pk_bf16_f32 v71, v62, v63
	v_lshl_add_u64 v[66:67], v[66:67], 1, v[80:81]
	v_cmp_ne_u32_e64 s[2:3], 1, v65
	s_andn2_b64 vcc, exec, s[28:29]
	v_lshl_add_u64 v[82:83], s[0:1], 0, v[74:75]
	v_lshlrev_b32_e32 v108, 2, v76
	v_or_b32_e32 v78, 0x200, v74
	v_or_b32_e32 v76, 0x400, v74
	v_or_b32_e32 v74, 0x600, v74
	global_store_dwordx2 v[66:67], v[70:71], off
	s_cbranch_vccnz .LBB0_201
	v_lshl_add_u64 v[68:69], v[82:83], 0, v[108:109]
	v_lshlrev_b32_e32 v70, 2, v84
	v_mov_b32_e32 v71, v109
	v_lshl_add_u64 v[68:69], v[68:69], 0, v[70:71]
	v_add_co_u32_e32 v68, vcc, 0xaa00000, v68
	v_mov_b32_e32 v79, v75
	s_nop 0
	v_addc_co_u32_e32 v69, vcc, 0, v69, vcc
	global_store_dword v[68:69], v60, off
	v_lshl_add_u64 v[68:69], s[0:1], 0, v[78:79]
	v_lshl_add_u64 v[68:69], v[68:69], 0, v[108:109]
	v_lshl_add_u64 v[68:69], v[68:69], 0, v[70:71]
	v_add_co_u32_e32 v68, vcc, 0xaa00000, v68
	v_mov_b32_e32 v77, v75
	s_nop 0
	v_addc_co_u32_e32 v69, vcc, 0, v69, vcc
	global_store_dword v[68:69], v61, off
	v_lshl_add_u64 v[68:69], s[0:1], 0, v[76:77]
	v_lshl_add_u64 v[68:69], v[68:69], 0, v[108:109]
	v_lshl_add_u64 v[68:69], v[68:69], 0, v[70:71]
	v_add_co_u32_e32 v68, vcc, 0xaa00000, v68
	s_nop 1
	v_addc_co_u32_e32 v69, vcc, 0, v69, vcc
	global_store_dword v[68:69], v62, off
	v_lshl_add_u64 v[68:69], s[0:1], 0, v[74:75]
	v_lshl_add_u64 v[68:69], v[68:69], 0, v[108:109]
	v_lshl_add_u64 v[68:69], v[68:69], 0, v[70:71]
	v_add_co_u32_e32 v68, vcc, 0xaa00000, v68
	s_nop 1
	v_addc_co_u32_e32 v69, vcc, 0, v69, vcc
	global_store_dword v[68:69], v63, off

.LBB0_892:
	s_lshl_b32 s2, s22, 12
	s_and_b32 s58, s5, 7
	s_addk_i32 s2, 0x1000
	s_lshl_b32 s3, s22, 8
	s_and_b64 s[0:1], s[0:1], exec
	s_cselect_b32 s0, s2, s3
	s_lshl_b32 s1, s4, 7
	s_add_i32 s0, s0, s1
	s_add_u32 s4, s64, s20
	v_lshl_or_b32 v0, v127, 5, v128
	s_addc_u32 s5, s60, s21
	s_ashr_i32 s23, s22, 31
	v_add_u32_e32 v126, s0, v0
	s_lshl_b64 s[0:1], s[22:23], 3
	s_or_b32 s70, s0, s58
	s_mul_hi_u32 s3, s55, s70
	s_mul_i32 s6, s55, s1
	s_mul_i32 s2, s55, s70
	s_add_i32 s3, s3, s6
	s_lshl_b64 s[2:3], s[2:3], 7
	s_add_u32 s90, s4, s2
	s_addc_u32 s91, s5, s3
	s_add_u32 s2, s64, s24
	s_addc_u32 s3, s60, s25
	s_lshl_b32 s71, s55, 6
	s_mul_i32 s69, s71, s22
	s_mul_hi_i32 s68, s71, s22
	s_add_u32 s30, s2, s69
	s_addc_u32 s31, s3, s68
	v_readlane_b32 s2, v215, 54
	v_readlane_b32 s3, v215, 55
	v_mov_b32_e32 v130, v111
	s_lshl_b32 s28, s58, 7
	v_mov_b64_e32 v[0:1], s[2:3]
	v_mad_i64_i32 v[0:1], s[2:3], v126, s83, v[0:1]
	s_mov_b32 s29, s87
	v_lshl_add_u64 v[2:3], v[0:1], 0, s[28:29]
	v_bfe_u32 v53, v130, 5, 1
	v_lshlrev_b32_e32 v128, 4, v53
	v_mov_b32_e32 v129, v109
	s_lshl_b32 s86, s58, 6
	v_lshl_add_u64 v[2:3], v[2:3], 0, v[128:129]
	v_lshl_add_u64 v[0:1], v[0:1], 0, s[86:87]
	global_load_dwordx4 v[20:23], v[2:3], off
	global_load_dwordx4 v[16:19], v[2:3], off offset:32
	global_load_dwordx4 v[12:15], v[2:3], off offset:64
	global_load_dwordx4 v[8:11], v[2:3], off offset:96
	v_lshl_add_u64 v[0:1], v[0:1], 0, v[128:129]
	global_load_dwordx4 v[4:7], v[0:1], off offset:1024
	s_nop 0
	global_load_dwordx4 v[0:3], v[0:1], off offset:1056
	v_mul_hi_i32 v24, v130, s75
	v_lshrrev_b32_e32 v25, 31, v24
	v_ashrrev_i32_e32 v24, 1, v24
	v_add_u32_e32 v36, v24, v25
	v_mul_lo_u32 v24, v36, 12
	v_sub_u32_e32 v55, v130, v24
	v_ashrrev_i32_e32 v37, 31, v36
	v_cmp_gt_i32_e32 vcc, 8, v55
	v_cmp_lt_i32_e64 s[6:7], 7, v55
	v_lshlrev_b32_e32 v34, 3, v55
	v_lshlrev_b64 v[38:39], 6, v[36:37]
	s_and_saveexec_b64 s[2:3], s[6:7]
	s_xor_b64 s[2:3], exec, s[2:3]
	v_lshl_add_u64 v[24:25], s[30:31], 0, v[38:39]
	v_mov_b32_e32 v35, v109
	s_movk_i32 s4, 0xff80
	v_lshl_add_u64 v[24:25], v[34:35], 1, v[24:25]
	s_mov_b32 s5, -1
	v_lshl_add_u64 v[24:25], v[24:25], 0, s[4:5]
	s_or_saveexec_b64 s[2:3], s[2:3]
	v_lshlrev_b64 v[32:33], 7, v[36:37]
	v_ashrrev_i32_e32 v37, 31, v34
	s_xor_b64 exec, exec, s[2:3]
	v_lshl_add_u64 v[24:25], s[90:91], 0, v[32:33]
	v_mov_b32_e32 v35, v37
	v_lshl_add_u64 v[24:25], v[34:35], 1, v[24:25]
	s_or_b64 exec, exec, s[2:3]
	global_load_dwordx4 v[24:27], v[24:25], off
	v_add_u32_e32 v52, 0x100, v130
	v_mul_hi_i32 v28, v52, s75
	v_lshrrev_b32_e32 v29, 31, v28
	v_ashrrev_i32_e32 v28, 1, v28
	v_add_u32_e32 v42, v28, v29
	v_mul_lo_u32 v28, v42, 12
	v_sub_u32_e32 v35, v52, v28
	v_ashrrev_i32_e32 v43, 31, v42
	v_cmp_gt_i32_e64 s[2:3], 8, v35
	v_cmp_lt_i32_e64 s[8:9], 7, v35
	v_lshlrev_b32_e32 v44, 3, v35
	v_lshlrev_b64 v[46:47], 6, v[42:43]
	s_and_saveexec_b64 s[4:5], s[8:9]
	s_xor_b64 s[4:5], exec, s[4:5]
	v_lshl_add_u64 v[28:29], s[30:31], 0, v[46:47]
	v_mov_b32_e32 v45, v109
	s_movk_i32 s10, 0xff80
	v_lshl_add_u64 v[28:29], v[44:45], 1, v[28:29]
	s_mov_b32 s11, -1
	v_lshl_add_u64 v[28:29], v[28:29], 0, s[10:11]
	s_or_saveexec_b64 s[4:5], s[4:5]
	v_lshlrev_b64 v[40:41], 7, v[42:43]
	v_ashrrev_i32_e32 v43, 31, v44
	s_xor_b64 exec, exec, s[4:5]
	v_lshl_add_u64 v[28:29], s[90:91], 0, v[40:41]
	v_mov_b32_e32 v45, v43
	v_lshl_add_u64 v[28:29], v[44:45], 1, v[28:29]
	s_or_b64 exec, exec, s[4:5]
	global_load_dwordx4 v[28:31], v[28:29], off
	v_add_u32_e32 v45, 0x200, v130
	v_mul_hi_i32 v48, v45, s75
	v_lshrrev_b32_e32 v49, 31, v48
	v_ashrrev_i32_e32 v48, 1, v48
	v_add_u32_e32 v60, v48, v49
	v_mul_lo_u32 v48, v60, 12
	v_sub_u32_e32 v45, v45, v48
	v_ashrrev_i32_e32 v61, 31, v60
	v_cmp_gt_i32_e64 s[4:5], 8, v45
	v_cmp_lt_i32_e64 s[10:11], 7, v45
	v_lshlrev_b32_e32 v108, 3, v45
	v_lshlrev_b64 v[48:49], 6, v[60:61]
	s_and_saveexec_b64 s[72:73], s[10:11]
	s_xor_b64 s[92:93], exec, s[72:73]
	v_lshlrev_b64 v[50:51], 6, v[60:61]
	v_lshl_add_u64 v[50:51], s[30:31], 0, v[50:51]
	s_movk_i32 s36, 0xff80
	v_lshl_add_u64 v[50:51], v[108:109], 1, v[50:51]
	s_mov_b32 s37, -1
	v_lshl_add_u64 v[64:65], v[50:51], 0, s[36:37]
	s_or_saveexec_b64 s[92:93], s[92:93]
	v_ashrrev_i32_e32 v63, 31, v108
	v_lshlrev_b64 v[50:51], 7, v[60:61]
	s_xor_b64 exec, exec, s[92:93]
	v_lshlrev_b64 v[56:57], 7, v[60:61]
	v_lshl_add_u64 v[56:57], s[90:91], 0, v[56:57]
	v_mov_b32_e32 v62, v108
	v_lshl_add_u64 v[64:65], v[62:63], 1, v[56:57]
	s_or_b64 exec, exec, s[92:93]
	s_add_u32 s29, s64, s26
	s_mul_i32 s72, s1, s71
	s_mul_hi_u32 s73, s70, s71
	s_addc_u32 s74, s60, s27
	s_add_i32 s73, s73, s72
	s_mul_i32 s72, s70, s71
	s_lshl_b64 s[70:71], s[72:73], 1
	s_add_u32 s70, s29, s70
	v_ashrrev_i32_e32 v54, 3, v130
	v_lshlrev_b32_e32 v58, 4, v130
	v_ashrrev_i32_e32 v52, 3, v52
	s_addc_u32 s71, s74, s71
	v_mad_i64_i32 v[56:57], s[72:73], v54, s55, 0
	v_and_b32_e32 v124, 0x70, v58
	v_mad_i64_i32 v[58:59], s[72:73], v52, s55, 0
	v_lshl_add_u64 v[56:57], v[56:57], 1, s[70:71]
	v_mov_b32_e32 v125, v109
	v_lshl_add_u64 v[58:59], v[58:59], 1, s[70:71]
	s_movk_i32 s29, 0xd0
	v_lshl_add_u64 v[56:57], v[56:57], 0, v[124:125]
	v_lshl_add_u64 v[58:59], v[58:59], 0, v[124:125]
	v_mul_lo_u32 v123, v36, s29
	v_lshlrev_b32_e32 v125, 4, v55
	v_add_u32_e32 v36, v123, v125
	v_mul_lo_u32 v129, v42, s29
	v_lshlrev_b32_e32 v166, 4, v35
	s_waitcnt vmcnt(1)
	ds_write_b128 v36, v[24:27]
	v_add_u32_e32 v24, v129, v166
	s_waitcnt vmcnt(0)
	ds_write_b128 v24, v[28:31]
	global_load_dwordx4 v[24:27], v[64:65], off
	global_load_dwordx4 v[66:69], v[56:57], off
	global_load_dwordx4 v[70:73], v[58:59], off
	v_mul_lo_u32 v167, v60, s29
	v_lshlrev_b32_e32 v168, 4, v45
	s_movk_i32 s29, 0x88
	s_add_u32 s90, s90, 0x2000
	v_add_u32_e32 v28, v167, v168
	v_mul_lo_u32 v169, v54, s29
	s_addc_u32 s91, s91, 0
	v_mul_lo_u32 v170, v52, s29
	s_add_u32 s30, s30, 0x1000
	s_movk_i32 s74, 0xd0
	s_addc_u32 s31, s31, 0
	s_waitcnt vmcnt(2)
	ds_write_b128 v28, v[24:27]
	v_add3_u32 v24, v169, v124, s63
	s_waitcnt vmcnt(1)
	ds_write2_b64 v24, v[66:67], v[68:69] offset1:1
	v_add3_u32 v24, v170, v124, s63
	s_waitcnt vmcnt(0)
	ds_write2_b64 v24, v[70:71], v[72:73] offset1:1
	s_and_saveexec_b64 s[70:71], s[6:7]
	s_xor_b64 s[6:7], exec, s[70:71]
	s_mov_b32 s75, 0x2aaaaaab
	v_lshl_add_u64 v[24:25], s[30:31], 0, v[38:39]
	v_mov_b32_e32 v35, v109
	s_movk_i32 s36, 0xff80
	v_lshl_add_u64 v[24:25], v[34:35], 1, v[24:25]
	s_mov_b32 s37, -1
	v_lshl_add_u64 v[24:25], v[24:25], 0, s[36:37]
	s_andn2_saveexec_b64 s[6:7], s[6:7]
	v_lshl_add_u64 v[24:25], s[90:91], 0, v[32:33]
	v_mov_b32_e32 v35, v37
	v_lshl_add_u64 v[24:25], v[34:35], 1, v[24:25]
	s_or_b64 exec, exec, s[6:7]
	global_load_dwordx4 v[64:67], v[24:25], off
	s_and_saveexec_b64 s[6:7], s[8:9]
	s_xor_b64 s[6:7], exec, s[6:7]
	v_lshl_add_u64 v[24:25], s[30:31], 0, v[46:47]
	v_mov_b32_e32 v45, v109
	s_movk_i32 s8, 0xff80
	v_lshl_add_u64 v[24:25], v[44:45], 1, v[24:25]
	s_mov_b32 s9, -1
	v_lshl_add_u64 v[24:25], v[24:25], 0, s[8:9]
	s_andn2_saveexec_b64 s[6:7], s[6:7]
	v_lshl_add_u64 v[24:25], s[90:91], 0, v[40:41]
	v_mov_b32_e32 v45, v43
	v_lshl_add_u64 v[24:25], v[44:45], 1, v[24:25]
	s_or_b64 exec, exec, s[6:7]
	global_load_dwordx4 v[76:79], v[24:25], off
	s_and_saveexec_b64 s[6:7], s[10:11]
	s_xor_b64 s[6:7], exec, s[6:7]
	v_lshlrev_b64 v[48:49], 6, v[60:61]
	v_lshl_add_u64 v[24:25], s[30:31], 0, v[48:49]
	s_movk_i32 s8, 0xff80
	v_lshl_add_u64 v[24:25], v[108:109], 1, v[24:25]
	s_mov_b32 s9, -1
	v_lshl_add_u64 v[26:27], v[24:25], 0, s[8:9]
	v_lshlrev_b64 v[50:51], 7, v[60:61]
	s_or_saveexec_b64 s[6:7], s[6:7]
	v_mov_b64_e32 v[24:25], v[108:109]
	s_xor_b64 exec, exec, s[6:7]
	v_lshl_add_u64 v[24:25], s[90:91], 0, v[50:51]
	v_mov_b32_e32 v62, v108
	v_lshl_add_u64 v[26:27], v[62:63], 1, v[24:25]
	v_mov_b64_e32 v[24:25], v[62:63]
	s_or_b64 exec, exec, s[6:7]
	global_load_dwordx4 v[96:99], v[26:27], off
	global_load_dwordx4 v[100:103], v[56:57], off offset:128
	global_load_dwordx4 v[104:107], v[58:59], off offset:128
	s_lshr_b32 s7, s55, 6
	v_lshlrev_b32_e32 v28, 16, v20
	v_and_b32_e32 v29, 0xffff0000, v20
	s_mov_b32 s6, 0x3e16c740
	v_lshlrev_b32_e32 v20, 16, v21
	v_and_b32_e32 v21, 0xffff0000, v21
	v_pk_mul_f32 v[20:21], v[20:21], s[6:7] op_sel_hi:[1,0]
	s_lshl_b64 s[8:9], s[22:23], 10
	v_cvt_pk_bf16_f32 v69, v20, v21
	v_lshlrev_b32_e32 v20, 16, v22
	v_and_b32_e32 v21, 0xffff0000, v22
	v_pk_mul_f32 v[20:21], v[20:21], s[6:7] op_sel_hi:[1,0]
	v_ashrrev_i32_e32 v55, 31, v54
	v_cvt_pk_bf16_f32 v70, v20, v21
	v_lshlrev_b32_e32 v20, 16, v23
	v_and_b32_e32 v21, 0xffff0000, v23
	v_pk_mul_f32 v[20:21], v[20:21], s[6:7] op_sel_hi:[1,0]
	s_or_b32 s8, s8, s28
	v_cvt_pk_bf16_f32 v71, v20, v21
	v_lshlrev_b32_e32 v20, 16, v16
	v_and_b32_e32 v21, 0xffff0000, v16
	v_lshlrev_b32_e32 v16, 16, v17
	v_and_b32_e32 v17, 0xffff0000, v17
	v_pk_mul_f32 v[16:17], v[16:17], s[6:7] op_sel_hi:[1,0]
	v_readlane_b32 s36, v215, 6
	v_cvt_pk_bf16_f32 v73, v16, v17
	v_lshlrev_b32_e32 v16, 16, v18
	v_and_b32_e32 v17, 0xffff0000, v18
	v_pk_mul_f32 v[16:17], v[16:17], s[6:7] op_sel_hi:[1,0]
	v_lshlrev_b32_e32 v122, 3, v53
	v_cvt_pk_bf16_f32 v74, v16, v17
	v_lshlrev_b32_e32 v16, 16, v19
	v_and_b32_e32 v17, 0xffff0000, v19
	v_pk_mul_f32 v[16:17], v[16:17], s[6:7] op_sel_hi:[1,0]
	v_ashrrev_i32_e32 v53, 31, v52
	v_cvt_pk_bf16_f32 v75, v16, v17
	v_lshlrev_b32_e32 v16, 16, v12
	v_and_b32_e32 v17, 0xffff0000, v12
	v_lshlrev_b32_e32 v12, 16, v13
	v_and_b32_e32 v13, 0xffff0000, v13
	v_pk_mul_f32 v[12:13], v[12:13], s[6:7] op_sel_hi:[1,0]
	v_readlane_b32 s50, v215, 20
	v_cvt_pk_bf16_f32 v85, v12, v13
	v_lshlrev_b32_e32 v12, 16, v14
	v_and_b32_e32 v13, 0xffff0000, v14
	v_pk_mul_f32 v[12:13], v[12:13], s[6:7] op_sel_hi:[1,0]
	v_readlane_b32 s51, v215, 21
	v_cvt_pk_bf16_f32 v86, v12, v13
	v_lshlrev_b32_e32 v12, 16, v15
	v_and_b32_e32 v13, 0xffff0000, v15
	v_pk_mul_f32 v[12:13], v[12:13], s[6:7] op_sel_hi:[1,0]
	v_pk_mul_f32 v[28:29], v[28:29], s[6:7] op_sel_hi:[1,0]
	v_cvt_pk_bf16_f32 v87, v12, v13
	v_lshlrev_b32_e32 v12, 16, v8
	v_and_b32_e32 v13, 0xffff0000, v8
	v_lshlrev_b32_e32 v8, 16, v9
	v_and_b32_e32 v9, 0xffff0000, v9
	v_pk_mul_f32 v[8:9], v[8:9], s[6:7] op_sel_hi:[1,0]
	v_pk_mul_f32 v[20:21], v[20:21], s[6:7] op_sel_hi:[1,0]
	v_cvt_pk_bf16_f32 v81, v8, v9
	v_lshlrev_b32_e32 v8, 16, v10
	v_and_b32_e32 v9, 0xffff0000, v10
	v_pk_mul_f32 v[8:9], v[8:9], s[6:7] op_sel_hi:[1,0]
	v_pk_mul_f32 v[16:17], v[16:17], s[6:7] op_sel_hi:[1,0]
	v_cvt_pk_bf16_f32 v82, v8, v9
	v_lshlrev_b32_e32 v8, 16, v11
	v_and_b32_e32 v9, 0xffff0000, v11
	v_pk_mul_f32 v[8:9], v[8:9], s[6:7] op_sel_hi:[1,0]
	v_pk_mul_f32 v[12:13], v[12:13], s[6:7] op_sel_hi:[1,0]
	v_cvt_pk_bf16_f32 v83, v8, v9
	v_lshlrev_b32_e32 v8, 16, v4
	v_and_b32_e32 v9, 0xffff0000, v4
	v_lshlrev_b32_e32 v4, 16, v5
	v_and_b32_e32 v5, 0xffff0000, v5
	v_pk_mul_f32 v[4:5], v[4:5], s[6:7] op_sel_hi:[1,0]
	v_pk_mul_f32 v[8:9], v[8:9], s[6:7] op_sel_hi:[1,0]
	v_cvt_pk_bf16_f32 v93, v4, v5
	v_lshlrev_b32_e32 v4, 16, v6
	v_and_b32_e32 v5, 0xffff0000, v6
	v_pk_mul_f32 v[4:5], v[4:5], s[6:7] op_sel_hi:[1,0]
	v_mov_b32_e32 v35, v109
	v_cvt_pk_bf16_f32 v94, v4, v5
	v_lshlrev_b32_e32 v4, 16, v7
	v_and_b32_e32 v5, 0xffff0000, v7
	v_pk_mul_f32 v[4:5], v[4:5], s[6:7] op_sel_hi:[1,0]
	v_mov_b32_e32 v45, v109
	v_cvt_pk_bf16_f32 v95, v4, v5
	v_lshlrev_b32_e32 v4, 16, v0
	v_and_b32_e32 v5, 0xffff0000, v0
	v_lshlrev_b32_e32 v0, 16, v1
	v_and_b32_e32 v1, 0xffff0000, v1
	v_pk_mul_f32 v[0:1], v[0:1], s[6:7] op_sel_hi:[1,0]
	v_pk_mul_f32 v[4:5], v[4:5], s[6:7] op_sel_hi:[1,0]
	v_cvt_pk_bf16_f32 v89, v0, v1
	v_lshlrev_b32_e32 v0, 16, v2
	v_and_b32_e32 v1, 0xffff0000, v2
	v_pk_mul_f32 v[0:1], v[0:1], s[6:7] op_sel_hi:[1,0]
	v_cvt_pk_bf16_f32 v88, v4, v5
	v_cvt_pk_bf16_f32 v90, v0, v1
	v_lshlrev_b32_e32 v0, 16, v3
	v_and_b32_e32 v1, 0xffff0000, v3
	v_pk_mul_f32 v[0:1], v[0:1], s[6:7] op_sel_hi:[1,0]
	v_mov_b64_e32 v[2:3], s[26:27]
	v_cvt_pk_bf16_f32 v91, v0, v1
	v_and_b32_e32 v0, 31, v130
	v_mul_u32_u24_e32 v176, 0xd0, v0
	v_mul_u32_u24_e32 v175, 0x88, v0
	v_lshl_add_u64 v[0:1], v[54:55], 1, s[8:9]
	v_mad_u64_u32 v[4:5], s[10:11], v0, s55, v[2:3]
	v_and_b32_e32 v0, 7, v130
	v_mad_i32_i24 v5, v1, s55, v5
	v_lshlrev_b32_e32 v0, 4, v0
	v_mov_b32_e32 v1, v109
	v_lshl_add_u64 v[4:5], v[4:5], 0, v[0:1]
	v_lshl_add_u64 v[130:131], s[50:51], 0, v[4:5]
	v_lshl_add_u64 v[4:5], v[52:53], 1, s[8:9]
	s_add_i32 s7, s7, -2
	v_mad_u64_u32 v[2:3], s[8:9], v4, s55, v[2:3]
	s_add_u32 s8, s24, s69
	v_mad_i32_i24 v3, v5, s55, v3
	s_addc_u32 s9, s25, s68
	v_lshl_add_u64 v[0:1], v[2:3], 0, v[0:1]
	s_add_u32 s0, s0, s58
	v_lshl_add_u64 v[132:133], s[50:51], 0, v[0:1]
	v_lshl_add_u64 v[0:1], s[8:9], 0, v[38:39]
	v_readlane_b32 s10, v215, 4
	s_addc_u32 s1, s1, 0
	v_lshl_add_u64 v[0:1], v[34:35], 1, v[0:1]
	v_readlane_b32 s11, v215, 5
	s_mul_i32 s1, s1, s55
	s_mul_hi_u32 s6, s0, s55
	v_lshl_add_u64 v[134:135], s[10:11], 0, v[0:1]
	v_lshl_add_u64 v[0:1], s[8:9], 0, v[46:47]
	s_add_i32 s1, s6, s1
	s_mul_i32 s0, s0, s55
	v_lshl_add_u64 v[0:1], v[44:45], 1, v[0:1]
	s_lshl_b64 s[0:1], s[0:1], 7
	v_lshl_add_u64 v[136:137], s[10:11], 0, v[0:1]
	v_lshl_add_u64 v[0:1], s[8:9], 0, v[48:49]
	s_add_u32 s0, s20, s0
	v_lshl_add_u64 v[0:1], v[108:109], 1, v[0:1]
	s_addc_u32 s1, s21, s1
	v_mov_b32_e32 v36, v34
	v_lshl_add_u64 v[138:139], s[10:11], 0, v[0:1]
	v_lshl_add_u64 v[0:1], s[0:1], 0, v[32:33]
	v_readlane_b32 s8, v215, 22
	v_lshl_add_u64 v[0:1], v[36:37], 1, v[0:1]
	v_readlane_b32 s9, v215, 23
	v_mov_b32_e32 v42, v44
	v_mov_b32_e32 v177, 0
	v_lshl_add_u64 v[140:141], s[8:9], 0, v[0:1]
	v_lshl_add_u64 v[0:1], s[0:1], 0, v[40:41]
	v_lshl_add_u64 v[0:1], v[42:43], 1, v[0:1]
	v_lshl_add_u64 v[142:143], s[8:9], 0, v[0:1]
	v_lshl_add_u64 v[0:1], s[0:1], 0, v[50:51]
	v_lshl_add_u64 v[0:1], v[24:25], 1, v[0:1]
	v_ashrrev_i32_e32 v127, 31, v126
	v_cvt_pk_bf16_f32 v68, v28, v29
	v_cvt_pk_bf16_f32 v72, v20, v21
	v_cvt_pk_bf16_f32 v84, v16, v17
	v_cvt_pk_bf16_f32 v80, v12, v13
	v_cvt_pk_bf16_f32 v92, v8, v9
	v_lshl_add_u64 v[144:145], s[8:9], 0, v[0:1]
	s_mov_b32 s8, 0
	v_mov_b32_e32 v108, 0xf149f2ca
	v_mov_b32_e32 v16, 0
	v_mov_b32_e32 v17, v177
	v_mov_b32_e32 v18, v177
	v_mov_b32_e32 v19, v177
	v_mov_b32_e32 v20, v177
	v_mov_b32_e32 v21, v177
	v_mov_b32_e32 v22, v177
	v_mov_b32_e32 v23, v177
	v_mov_b32_e32 v24, v177
	v_mov_b32_e32 v25, v177
	v_mov_b32_e32 v26, v177
	v_mov_b32_e32 v27, v177
	v_mov_b32_e32 v28, v177
	v_mov_b32_e32 v29, v177
	v_mov_b32_e32 v30, v177
	v_mov_b32_e32 v31, v177
	v_mov_b32_e32 v0, 0
	v_mov_b32_e32 v1, v177
	v_mov_b32_e32 v2, v177
	v_mov_b32_e32 v3, v177
	v_mov_b32_e32 v4, v177
	v_mov_b32_e32 v5, v177
	v_mov_b32_e32 v6, v177
	v_mov_b32_e32 v7, v177
	v_mov_b32_e32 v8, v177
	v_mov_b32_e32 v9, v177
	v_mov_b32_e32 v10, v177
	v_mov_b32_e32 v11, v177
	v_mov_b32_e32 v12, v177
	v_mov_b32_e32 v13, v177
	v_mov_b32_e32 v14, v177
	v_mov_b32_e32 v15, v177
	s_waitcnt lgkmcnt(0)
	s_barrier
	v_readlane_b32 s37, v215, 7
	v_readlane_b32 s38, v215, 8
	v_readlane_b32 s39, v215, 9
	v_readlane_b32 s40, v215, 10
	v_readlane_b32 s41, v215, 11
	v_readlane_b32 s42, v215, 12
	v_readlane_b32 s43, v215, 13
	v_readlane_b32 s44, v215, 14
	v_readlane_b32 s45, v215, 15
	v_readlane_b32 s46, v215, 16
	v_readlane_b32 s47, v215, 17
	v_readlane_b32 s48, v215, 18
	v_readlane_b32 s49, v215, 19
	v_mov_b32_e32 v108, 0
	v_mov_b32_e32 v240, 0
	v_mov_b32_e32 v241, 0
	v_mov_b32_e32 v242, 0
	v_mov_b32_e32 v243, 0
	v_mov_b32_e32 v244, 0
	v_mov_b32_e32 v245, 0
	v_mov_b32_e32 v246, 0
	v_mov_b32_e32 v247, 0
	v_mov_b32_e32 v248, 0
	v_mov_b32_e32 v249, 0
	v_mov_b32_e32 v250, 0
	v_mov_b32_e32 v251, 0
	v_mov_b32_e32 v252, 0
	v_mov_b32_e32 v253, 0
	v_mov_b32_e32 v254, 0
	v_mov_b32_e32 v255, 0
.LBB0_917:
	s_bitcmp1_b32 s8, 0
	s_cselect_b32 s6, 0x5800, 0
	v_add_u32_e32 v32, s6, v176
	v_add_u32_e32 v173, v32, v128
	ds_read_b128 v[220:223], v173
	ds_read_b128 v[224:227], v173 offset:6656
	ds_read_b128 v[228:231], v173 offset:32
	ds_read_b128 v[232:235], v173 offset:6688
	ds_read_b128 v[236:239], v173 offset:64
	ds_read_b128 v[184:187], v173 offset:6720
	v_add_u32_e32 v174, s6, v175
	v_add_u32_e32 v174, v174, v122
	v_add_u32_e32 v172, 0x4000, v174
	v_add_u32_e32 v174, 0x3000, v174
	s_waitcnt lgkmcnt(5)
	v_mfma_f32_32x32x16_bf16 v[48:63], v[220:223], v[68:71], v[240:255]
	s_waitcnt lgkmcnt(4)
	v_mfma_f32_32x32x16_bf16 v[32:47], v[224:227], v[68:71], v[240:255]
	ds_read_b128 v[220:223], v173 offset:96
	ds_read_b128 v[224:227], v173 offset:6752
	s_waitcnt lgkmcnt(5)
	v_mfma_f32_32x32x16_bf16 v[48:63], v[228:231], v[72:75], v[48:63]
	s_waitcnt lgkmcnt(4)
	v_mfma_f32_32x32x16_bf16 v[32:47], v[232:235], v[72:75], v[32:47]
	ds_read_b128 v[228:231], v173 offset:128
	ds_read_b128 v[232:235], v173 offset:6784
	s_waitcnt lgkmcnt(5)
	v_mfma_f32_32x32x16_bf16 v[48:63], v[236:239], v[84:87], v[48:63]
	s_waitcnt lgkmcnt(4)
	v_mfma_f32_32x32x16_bf16 v[32:47], v[184:187], v[84:87], v[32:47]
	ds_read_b128 v[236:239], v173 offset:160
	ds_read_b128 v[184:187], v173 offset:6816
	s_waitcnt lgkmcnt(5)
	v_mfma_f32_32x32x16_bf16 v[48:63], v[220:223], v[80:83], v[48:63]
	s_waitcnt lgkmcnt(4)
	v_mfma_f32_32x32x16_bf16 v[32:47], v[224:227], v[80:83], v[32:47]
	ds_read2_b64 v[220:223], v174 offset0:128 offset1:130
	ds_read2_b64 v[224:227], v172 offset0:160 offset1:162
	s_waitcnt lgkmcnt(5)
	v_mfma_f32_32x32x16_bf16 v[48:63], v[228:231], v[92:95], v[48:63]
	s_waitcnt lgkmcnt(4)
	v_mfma_f32_32x32x16_bf16 v[32:47], v[232:235], v[92:95], v[32:47]
	ds_read2_b64 v[228:231], v174 offset0:132 offset1:134
	ds_read2_b64 v[232:235], v172 offset0:164 offset1:166
	s_waitcnt lgkmcnt(5)
	v_mfma_f32_32x32x16_bf16 v[48:63], v[236:239], v[88:91], v[48:63]
	s_waitcnt lgkmcnt(4)
	v_mfma_f32_32x32x16_bf16 v[32:47], v[184:187], v[88:91], v[32:47]
	ds_read2_b64 v[236:239], v174 offset0:136 offset1:138
	ds_read2_b64 v[184:187], v172 offset0:168 offset1:170
	s_add_i32 s8, s8, 1
	s_bitcmp1_b32 s8, 0
	s_cselect_b32 s0, 0x5800, 0
	v_add3_u32 v179, s0, v123, v125
	s_waitcnt vmcnt(4)
	ds_write_b128 v179, v[64:67]
	v_add3_u32 v179, s0, v129, v166
	s_waitcnt vmcnt(3)
	ds_write_b128 v179, v[76:79]
	v_add3_u32 v179, s0, v167, v168
	s_waitcnt vmcnt(2)
	ds_write_b128 v179, v[96:99]
	v_add_u32_e32 v179, s0, v169
	v_add3_u32 v179, v179, v124, s63
	s_waitcnt vmcnt(1)
	ds_write2_b64 v179, v[100:101], v[102:103] offset1:1
	v_add_u32_e32 v179, s0, v170
	v_add3_u32 v179, v179, v124, s63
	s_waitcnt vmcnt(0)
	ds_write2_b64 v179, v[104:105], v[106:107] offset1:1
	v_max3_f32 v188, v48, v49, v50
	v_max3_f32 v189, v32, v33, v34
	v_max3_f32 v188, v188, v51, v52
	v_max3_f32 v189, v189, v35, v36
	v_max3_f32 v188, v188, v53, v54
	v_max3_f32 v189, v189, v37, v38
	v_max3_f32 v188, v188, v55, v56
	v_max3_f32 v189, v189, v39, v40
	v_max3_f32 v188, v188, v57, v58
	v_max3_f32 v189, v189, v41, v42
	v_max3_f32 v188, v188, v59, v60
	v_max3_f32 v189, v189, v43, v44
	v_max3_f32 v188, v188, v61, v62
	v_max3_f32 v189, v189, v45, v46
	v_max3_f32 v188, v188, v63, v47
	v_max_f32_e32 v217, v188, v189
	v_cmp_lt_f32_e64 s[98:99], 4.0, v217
	v_lshl_add_u64 v[180:181], v[140:141], 0, s[56:57]
	v_lshl_add_u64 v[182:183], v[134:135], 0, s[56:57]
	v_cndmask_b32_e32 v181, v183, v181, vcc
	v_cndmask_b32_e32 v180, v182, v180, vcc
	global_load_dwordx4 v[64:67], v[180:181], off
	v_lshl_add_u64 v[180:181], v[142:143], 0, s[56:57]
	v_lshl_add_u64 v[182:183], v[136:137], 0, s[56:57]
	v_cndmask_b32_e64 v181, v183, v181, s[2:3]
	v_cndmask_b32_e64 v180, v182, v180, s[2:3]
	global_load_dwordx4 v[76:79], v[180:181], off
	v_lshl_add_u64 v[180:181], v[144:145], 0, s[56:57]
	v_lshl_add_u64 v[182:183], v[138:139], 0, s[56:57]
	v_cndmask_b32_e64 v181, v183, v181, s[4:5]
	v_cndmask_b32_e64 v180, v182, v180, s[4:5]
	global_load_dwordx4 v[96:99], v[180:181], off
	v_lshl_add_u64 v[180:181], v[130:131], 0, s[56:57]
	global_load_dwordx4 v[100:103], v[180:181], off offset:256
	v_lshl_add_u64 v[180:181], v[132:133], 0, s[56:57]
	global_load_dwordx4 v[104:107], v[180:181], off offset:256
	v_lshl_add_u64 v[130:131], v[130:131], 0, s[12:13]
	v_lshl_add_u64 v[132:133], v[132:133], 0, s[12:13]
	v_lshl_add_u64 v[134:135], v[134:135], 0, s[34:35]
	v_lshl_add_u64 v[136:137], v[136:137], 0, s[34:35]
	v_lshl_add_u64 v[138:139], v[138:139], 0, s[34:35]
	v_lshl_add_u64 v[140:141], v[140:141], 0, s[76:77]
	v_lshl_add_u64 v[142:143], v[142:143], 0, s[76:77]
	v_lshl_add_u64 v[144:145], v[144:145], 0, s[76:77]
	s_cmp_eq_u64 s[98:99], 0
	s_cbranch_scc0 .Lmla_slow
.Lmla_fast:
	v_exp_f32_e32 v48, v48
	v_exp_f32_e32 v49, v49
	v_exp_f32_e32 v50, v50
	v_exp_f32_e32 v51, v51
	v_exp_f32_e32 v52, v52
	v_exp_f32_e32 v53, v53
	v_exp_f32_e32 v54, v54
	v_exp_f32_e32 v55, v55
	v_add_f32_e32 v218, v48, v49
	v_add_f32_e32 v219, v50, v51
	v_add_f32_e32 v218, v218, v52
	v_add_f32_e32 v219, v219, v53
	v_add_f32_e32 v218, v218, v54
	v_add_f32_e32 v219, v219, v55
	v_cvt_pk_bf16_f32 v48, v48, v49
	v_cvt_pk_bf16_f32 v49, v50, v51
	v_cvt_pk_bf16_f32 v50, v52, v53
	v_cvt_pk_bf16_f32 v51, v54, v55
	v_exp_f32_e32 v56, v56
	v_exp_f32_e32 v57, v57
	s_waitcnt lgkmcnt(0)
	v_mfma_f32_32x32x16_bf16 v[16:31], v[220:223], v[48:51], v[16:31]
	v_exp_f32_e32 v58, v58
	v_exp_f32_e32 v59, v59
	v_exp_f32_e32 v60, v60
	v_mfma_f32_32x32x16_bf16 v[0:15], v[224:227], v[48:51], v[0:15]
	ds_read2_b64 v[220:223], v174 offset0:140 offset1:142
	ds_read2_b64 v[224:227], v172 offset0:172 offset1:174
	v_exp_f32_e32 v61, v61
	v_exp_f32_e32 v62, v62
	v_exp_f32_e32 v63, v63
	v_add_f32_e32 v218, v218, v56
	v_add_f32_e32 v219, v219, v57
	v_add_f32_e32 v218, v218, v58
	v_add_f32_e32 v219, v219, v59
	v_add_f32_e32 v218, v218, v60
	v_add_f32_e32 v219, v219, v61
	v_add_f32_e32 v218, v218, v62
	v_add_f32_e32 v219, v219, v63
	v_cvt_pk_bf16_f32 v56, v56, v57
	v_cvt_pk_bf16_f32 v57, v58, v59
	v_cvt_pk_bf16_f32 v58, v60, v61
	v_cvt_pk_bf16_f32 v59, v62, v63
	v_exp_f32_e32 v32, v32
	v_exp_f32_e32 v33, v33
	v_mfma_f32_32x32x16_bf16 v[16:31], v[228:231], v[56:59], v[16:31]
	v_exp_f32_e32 v34, v34
	v_exp_f32_e32 v35, v35
	v_exp_f32_e32 v36, v36
	v_mfma_f32_32x32x16_bf16 v[0:15], v[232:235], v[56:59], v[0:15]
	v_exp_f32_e32 v37, v37
	v_exp_f32_e32 v38, v38
	v_exp_f32_e32 v39, v39
	v_add_f32_e32 v218, v218, v32
	v_add_f32_e32 v219, v219, v33
	v_add_f32_e32 v218, v218, v34
	v_add_f32_e32 v219, v219, v35
	v_add_f32_e32 v218, v218, v36
	v_add_f32_e32 v219, v219, v37
	v_add_f32_e32 v218, v218, v38
	v_add_f32_e32 v219, v219, v39
	v_cvt_pk_bf16_f32 v32, v32, v33
	v_cvt_pk_bf16_f32 v33, v34, v35
	v_cvt_pk_bf16_f32 v34, v36, v37
	v_cvt_pk_bf16_f32 v35, v38, v39
	v_exp_f32_e32 v40, v40
	v_exp_f32_e32 v41, v41
	v_mfma_f32_32x32x16_bf16 v[16:31], v[236:239], v[32:35], v[16:31]
	v_exp_f32_e32 v42, v42
	v_exp_f32_e32 v43, v43
	v_exp_f32_e32 v44, v44
	v_mfma_f32_32x32x16_bf16 v[0:15], v[184:187], v[32:35], v[0:15]
	v_exp_f32_e32 v45, v45
	v_exp_f32_e32 v46, v46
	v_exp_f32_e32 v47, v47
	v_add_f32_e32 v218, v218, v40
	v_add_f32_e32 v219, v219, v41
	v_add_f32_e32 v218, v218, v42
	v_add_f32_e32 v219, v219, v43
	v_add_f32_e32 v218, v218, v44
	v_add_f32_e32 v219, v219, v45
	v_add_f32_e32 v218, v218, v46
	v_add_f32_e32 v219, v219, v47
	v_cvt_pk_bf16_f32 v40, v40, v41
	v_cvt_pk_bf16_f32 v41, v42, v43
	v_cvt_pk_bf16_f32 v42, v44, v45
	v_cvt_pk_bf16_f32 v43, v46, v47
	v_add_f32_e32 v218, v218, v219
	v_add_f32_e32 v177, v177, v218
	s_waitcnt lgkmcnt(0)
	v_mfma_f32_32x32x16_bf16 v[16:31], v[220:223], v[40:43], v[16:31]
	v_mfma_f32_32x32x16_bf16 v[0:15], v[224:227], v[40:43], v[0:15]
	s_cmp_eq_u32 s7, s8
	s_waitcnt lgkmcnt(0)
	s_barrier
	s_cbranch_scc0 .LBB0_917
	v_mov_b32_e32 v188, v177
	v_cmp_lt_i32_e64 s[98:99], v153, v147
	s_nop 1
	v_permlane32_swap_b32_e32 v188, v177
	v_cndmask_b32_e64 v171, v146, v153, s[98:99]
	v_add_f32_e32 v177, v188, v177
	v_lshlrev_b32_e32 v171, 2, v171
	s_branch .Lmla_tail
.Lmla_slow:
	v_max_f32_e32 v217, 0, v217
	v_mov_b32_e32 v188, v217
	s_nop 1
	v_permlane32_swap_b32_e32 v188, v217
	v_max_f32_e32 v217, v188, v217
	v_sub_f32_e32 v188, 0, v217
	v_add_f32_e32 v108, v108, v217
	v_exp_f32_e32 v188, v188
	v_sub_f32_e32 v48, v48, v217
	v_sub_f32_e32 v49, v49, v217
	v_sub_f32_e32 v50, v50, v217
	v_sub_f32_e32 v51, v51, v217
	v_sub_f32_e32 v52, v52, v217
	v_sub_f32_e32 v53, v53, v217
	v_sub_f32_e32 v54, v54, v217
	v_sub_f32_e32 v55, v55, v217
	v_sub_f32_e32 v56, v56, v217
	v_sub_f32_e32 v57, v57, v217
	v_sub_f32_e32 v58, v58, v217
	v_sub_f32_e32 v59, v59, v217
	v_sub_f32_e32 v60, v60, v217
	v_sub_f32_e32 v61, v61, v217
	v_sub_f32_e32 v62, v62, v217
	v_sub_f32_e32 v63, v63, v217
	v_sub_f32_e32 v32, v32, v217
	v_sub_f32_e32 v33, v33, v217
	v_sub_f32_e32 v34, v34, v217
	v_sub_f32_e32 v35, v35, v217
	v_sub_f32_e32 v36, v36, v217
	v_sub_f32_e32 v37, v37, v217
	v_sub_f32_e32 v38, v38, v217
	v_sub_f32_e32 v39, v39, v217
	v_sub_f32_e32 v40, v40, v217
	v_sub_f32_e32 v41, v41, v217
	v_sub_f32_e32 v42, v42, v217
	v_sub_f32_e32 v43, v43, v217
	v_sub_f32_e32 v44, v44, v217
	v_sub_f32_e32 v45, v45, v217
	v_sub_f32_e32 v46, v46, v217
	v_sub_f32_e32 v47, v47, v217
	v_sub_f32_e32 v240, v240, v217
	v_sub_f32_e32 v241, v241, v217
	v_sub_f32_e32 v242, v242, v217
	v_sub_f32_e32 v243, v243, v217
	v_sub_f32_e32 v244, v244, v217
	v_sub_f32_e32 v245, v245, v217
	v_sub_f32_e32 v246, v246, v217
	v_sub_f32_e32 v247, v247, v217
	v_sub_f32_e32 v248, v248, v217
	v_sub_f32_e32 v249, v249, v217
	v_sub_f32_e32 v250, v250, v217
	v_sub_f32_e32 v251, v251, v217
	v_sub_f32_e32 v252, v252, v217
	v_sub_f32_e32 v253, v253, v217
	v_sub_f32_e32 v254, v254, v217
	v_sub_f32_e32 v255, v255, v217
	v_mul_f32_e32 v0, v0, v188
	v_mul_f32_e32 v1, v1, v188
	v_mul_f32_e32 v2, v2, v188
	v_mul_f32_e32 v3, v3, v188
	v_mul_f32_e32 v4, v4, v188
	v_mul_f32_e32 v5, v5, v188
	v_mul_f32_e32 v6, v6, v188
	v_mul_f32_e32 v7, v7, v188
	v_mul_f32_e32 v8, v8, v188
	v_mul_f32_e32 v9, v9, v188
	v_mul_f32_e32 v10, v10, v188
	v_mul_f32_e32 v11, v11, v188
	v_mul_f32_e32 v12, v12, v188
	v_mul_f32_e32 v13, v13, v188
	v_mul_f32_e32 v14, v14, v188
	v_mul_f32_e32 v15, v15, v188
	v_mul_f32_e32 v16, v16, v188
	v_mul_f32_e32 v17, v17, v188
	v_mul_f32_e32 v18, v18, v188
	v_mul_f32_e32 v19, v19, v188
	v_mul_f32_e32 v20, v20, v188
	v_mul_f32_e32 v21, v21, v188
	v_mul_f32_e32 v22, v22, v188
	v_mul_f32_e32 v23, v23, v188
	v_mul_f32_e32 v24, v24, v188
	v_mul_f32_e32 v25, v25, v188
	v_mul_f32_e32 v26, v26, v188
	v_mul_f32_e32 v27, v27, v188
	v_mul_f32_e32 v28, v28, v188
	v_mul_f32_e32 v29, v29, v188
	v_mul_f32_e32 v30, v30, v188
	v_mul_f32_e32 v31, v31, v188
	v_mul_f32_e32 v177, v177, v188
	s_branch .Lmla_fast
.Lmla_tail:
	v_add3_u32 v128, s0, v176, v128
	ds_read_b128 v[32:35], v128
	ds_read_b128 v[130:133], v128 offset:32
	v_readlane_b32 s2, v215, 56
	v_lshlrev_b64 v[126:127], 10, v[126:127]
	v_readlane_b32 s3, v215, 57
	s_lshl_b32 s86, s86, 1
	s_waitcnt lgkmcnt(1)
	v_mfma_f32_32x32x16_bf16 v[48:63], v[32:35], v[68:71], 0
	ds_read_b128 v[32:35], v128 offset:6656
	v_lshl_add_u64 v[126:127], s[2:3], 0, v[126:127]
	v_lshl_add_u64 v[126:127], v[126:127], 0, s[86:87]
	s_waitcnt lgkmcnt(1)
	v_mfma_f32_32x32x16_bf16 v[48:63], v[130:133], v[72:75], v[48:63]
	ds_read_b128 v[130:133], v128 offset:6688
	s_waitcnt lgkmcnt(1)
	v_mfma_f32_32x32x16_bf16 v[32:47], v[32:35], v[68:71], 0
	s_waitcnt lgkmcnt(0)
	v_mfma_f32_32x32x16_bf16 v[32:47], v[130:133], v[72:75], v[32:47]
	ds_read_b128 v[130:133], v128 offset:64
	s_waitcnt lgkmcnt(0)
	v_mfma_f32_32x32x16_bf16 v[48:63], v[130:133], v[84:87], v[48:63]
	ds_read_b128 v[130:133], v128 offset:6720
	s_waitcnt lgkmcnt(0)
	v_mfma_f32_32x32x16_bf16 v[32:47], v[130:133], v[84:87], v[32:47]
	ds_read_b128 v[130:133], v128 offset:96
	s_waitcnt lgkmcnt(0)
	v_mfma_f32_32x32x16_bf16 v[48:63], v[130:133], v[80:83], v[48:63]
	ds_read_b128 v[130:133], v128 offset:6752
	s_waitcnt lgkmcnt(0)
	v_mfma_f32_32x32x16_bf16 v[32:47], v[130:133], v[80:83], v[32:47]
	ds_read_b128 v[130:133], v128 offset:128
	s_waitcnt lgkmcnt(0)
	v_mfma_f32_32x32x16_bf16 v[48:63], v[130:133], v[92:95], v[48:63]
	ds_read_b128 v[130:133], v128 offset:6784
	s_waitcnt lgkmcnt(0)
	v_mfma_f32_32x32x16_bf16 v[32:47], v[130:133], v[92:95], v[32:47]
	ds_read_b128 v[130:133], v128 offset:160
	s_waitcnt lgkmcnt(0)
	v_mfma_f32_32x32x16_bf16 v[48:63], v[130:133], v[88:91], v[48:63]
	ds_read_b128 v[130:133], v128 offset:6816
	s_waitcnt lgkmcnt(0)
	v_mfma_f32_32x32x16_bf16 v[32:47], v[130:133], v[88:91], v[32:47]
	s_nop 11
	v_max_f32_e32 v128, v32, v32
	v_max_f32_e32 v130, v48, v48
	v_max_f32_e32 v128, v130, v128
	v_max_f32_e32 v130, v33, v33
	v_max_f32_e32 v131, v49, v49
	v_max_f32_e32 v130, v131, v130
	v_max3_f32 v128, v108, v128, v130
	v_max_f32_e32 v130, v34, v34
	v_max_f32_e32 v131, v50, v50
	v_max_f32_e32 v130, v131, v130
	v_max_f32_e32 v131, v35, v35
	v_max_f32_e32 v132, v51, v51
	v_max_f32_e32 v131, v132, v131
	v_max3_f32 v128, v128, v130, v131
	v_max_f32_e32 v130, v36, v36
	v_max_f32_e32 v131, v52, v52
	v_max_f32_e32 v130, v131, v130
	v_max_f32_e32 v131, v37, v37
	v_max_f32_e32 v132, v53, v53
	v_max_f32_e32 v131, v132, v131
	v_max3_f32 v128, v128, v130, v131
	v_max_f32_e32 v130, v38, v38
	v_max_f32_e32 v131, v54, v54
	v_max_f32_e32 v130, v131, v130
	v_max_f32_e32 v131, v39, v39
	v_max_f32_e32 v132, v55, v55
	v_max_f32_e32 v131, v132, v131
	v_max3_f32 v128, v128, v130, v131
	v_max_f32_e32 v130, v40, v40
	v_max_f32_e32 v131, v56, v56
	v_max_f32_e32 v130, v131, v130
	v_max_f32_e32 v131, v41, v41
	v_max_f32_e32 v132, v57, v57
	v_max_f32_e32 v131, v132, v131
	v_max3_f32 v128, v128, v130, v131
	v_max_f32_e32 v130, v42, v42
	v_max_f32_e32 v131, v58, v58
	v_max_f32_e32 v130, v131, v130
	v_max_f32_e32 v131, v43, v43
	v_max_f32_e32 v132, v59, v59
	v_max_f32_e32 v131, v132, v131
	v_max3_f32 v128, v128, v130, v131
	v_max_f32_e32 v130, v44, v44
	v_max_f32_e32 v131, v60, v60
	v_max_f32_e32 v130, v131, v130
	v_max_f32_e32 v131, v45, v45
	v_max_f32_e32 v132, v61, v61
	v_max_f32_e32 v131, v132, v131
	v_max3_f32 v128, v128, v130, v131
	v_max_f32_e32 v130, v46, v46
	v_max_f32_e32 v131, v62, v62
	v_max_f32_e32 v130, v131, v130
	v_max_f32_e32 v131, v47, v47
	v_max_f32_e32 v132, v63, v63
	v_max_f32_e32 v131, v132, v131
	v_max3_f32 v128, v128, v130, v131
	ds_bpermute_b32 v130, v171, v128
	v_add3_u32 v140, s0, v175, v122
	s_waitcnt lgkmcnt(0)
	v_max_f32_e32 v130, v130, v130
	v_max_f32_e32 v128, v128, v130
	v_pk_add_f32 v[48:49], v[48:49], v[128:129] op_sel_hi:[1,0] neg_lo:[0,1] neg_hi:[0,1]
	v_pk_add_f32 v[32:33], v[32:33], v[128:129] op_sel_hi:[1,0] neg_lo:[0,1] neg_hi:[0,1]
	v_exp_f32_e32 v130, v48
	v_exp_f32_e32 v131, v49
	v_exp_f32_e32 v32, v32
	v_exp_f32_e32 v33, v33
	v_pk_add_f32 v[48:49], v[50:51], v[128:129] op_sel_hi:[1,0] neg_lo:[0,1] neg_hi:[0,1]
	v_pk_add_f32 v[34:35], v[34:35], v[128:129] op_sel_hi:[1,0] neg_lo:[0,1] neg_hi:[0,1]
	v_exp_f32_e32 v132, v48
	v_exp_f32_e32 v133, v49
	v_exp_f32_e32 v48, v34
	v_exp_f32_e32 v49, v35
	v_pk_add_f32 v[50:51], v[52:53], v[128:129] op_sel_hi:[1,0] neg_lo:[0,1] neg_hi:[0,1]
	v_pk_add_f32 v[36:37], v[36:37], v[128:129] op_sel_hi:[1,0] neg_lo:[0,1] neg_hi:[0,1]
	v_exp_f32_e32 v136, v50
	v_exp_f32_e32 v137, v51
	v_exp_f32_e32 v50, v36
	v_exp_f32_e32 v51, v37
	v_pk_add_f32 v[34:35], v[32:33], v[130:131]
	v_pk_add_f32 v[134:135], v[48:49], v[132:133]
	v_pk_add_f32 v[34:35], v[34:35], 0 op_sel_hi:[1,0]
	v_pk_add_f32 v[36:37], v[54:55], v[128:129] op_sel_hi:[1,0] neg_lo:[0,1] neg_hi:[0,1]
	v_pk_add_f32 v[38:39], v[38:39], v[128:129] op_sel_hi:[1,0] neg_lo:[0,1] neg_hi:[0,1]
	v_exp_f32_e32 v54, v36
	v_exp_f32_e32 v55, v37
	v_pk_add_f32 v[34:35], v[134:135], v[34:35]
	v_pk_add_f32 v[36:37], v[50:51], v[136:137]
	v_exp_f32_e32 v52, v38
	v_exp_f32_e32 v53, v39
	v_pk_add_f32 v[38:39], v[36:37], v[34:35]
	v_pk_add_f32 v[34:35], v[56:57], v[128:129] op_sel_hi:[1,0] neg_lo:[0,1] neg_hi:[0,1]
	v_pk_add_f32 v[36:37], v[40:41], v[128:129] op_sel_hi:[1,0] neg_lo:[0,1] neg_hi:[0,1]
	v_exp_f32_e32 v138, v34
	v_exp_f32_e32 v139, v35
	v_exp_f32_e32 v34, v36
	v_exp_f32_e32 v35, v37
	v_pk_add_f32 v[134:135], v[52:53], v[54:55]
	v_pk_add_f32 v[36:37], v[58:59], v[128:129] op_sel_hi:[1,0] neg_lo:[0,1] neg_hi:[0,1]
	v_pk_add_f32 v[40:41], v[42:43], v[128:129] op_sel_hi:[1,0] neg_lo:[0,1] neg_hi:[0,1]
	v_exp_f32_e32 v58, v36
	v_exp_f32_e32 v59, v37
	v_exp_f32_e32 v36, v40
	v_exp_f32_e32 v37, v41
	v_pk_add_f32 v[38:39], v[134:135], v[38:39]
	v_pk_add_f32 v[40:41], v[34:35], v[138:139]
	v_pk_add_f32 v[44:45], v[44:45], v[128:129] op_sel_hi:[1,0] neg_lo:[0,1] neg_hi:[0,1]
	v_pk_add_f32 v[40:41], v[40:41], v[38:39]
	v_pk_add_f32 v[38:39], v[60:61], v[128:129] op_sel_hi:[1,0] neg_lo:[0,1] neg_hi:[0,1]
	v_pk_add_f32 v[46:47], v[46:47], v[128:129] op_sel_hi:[1,0] neg_lo:[0,1] neg_hi:[0,1]
	v_exp_f32_e32 v60, v38
	v_exp_f32_e32 v61, v39
	v_exp_f32_e32 v38, v44
	v_exp_f32_e32 v39, v45
	v_pk_add_f32 v[44:45], v[62:63], v[128:129] op_sel_hi:[1,0] neg_lo:[0,1] neg_hi:[0,1]
	v_exp_f32_e32 v134, v46
	v_exp_f32_e32 v62, v44
	v_exp_f32_e32 v63, v45
	v_exp_f32_e32 v135, v47
	v_pk_add_f32 v[42:43], v[36:37], v[58:59]
	v_sub_f32_e32 v108, v108, v128
	v_pk_add_f32 v[40:41], v[42:43], v[40:41]
	v_pk_add_f32 v[42:43], v[38:39], v[60:61]
	v_exp_f32_e32 v44, v108
	v_pk_add_f32 v[40:41], v[42:43], v[40:41]
	v_pk_add_f32 v[42:43], v[134:135], v[62:63]
	v_pk_mul_f32 v[30:31], v[30:31], v[44:45] op_sel_hi:[1,0]
	v_pk_add_f32 v[40:41], v[42:43], v[40:41]
	v_pk_mul_f32 v[28:29], v[28:29], v[44:45] op_sel_hi:[1,0]
	v_add_f32_e32 v40, v40, v41
	ds_bpermute_b32 v41, v171, v40
	v_pk_mul_f32 v[26:27], v[26:27], v[44:45] op_sel_hi:[1,0]
	v_pk_mul_f32 v[24:25], v[24:25], v[44:45] op_sel_hi:[1,0]
	v_pk_mul_f32 v[22:23], v[22:23], v[44:45] op_sel_hi:[1,0]
	v_pk_mul_f32 v[20:21], v[20:21], v[44:45] op_sel_hi:[1,0]
	s_waitcnt lgkmcnt(0)
	v_add_f32_e32 v108, v40, v41
	v_pk_mul_f32 v[18:19], v[18:19], v[44:45] op_sel_hi:[1,0]
	v_pk_mul_f32 v[16:17], v[16:17], v[44:45] op_sel_hi:[1,0]
	v_pk_mul_f32 v[14:15], v[14:15], v[44:45] op_sel_hi:[1,0]
	v_pk_mul_f32 v[12:13], v[12:13], v[44:45] op_sel_hi:[1,0]
	v_pk_mul_f32 v[10:11], v[10:11], v[44:45] op_sel_hi:[1,0]
	v_pk_mul_f32 v[8:9], v[8:9], v[44:45] op_sel_hi:[1,0]
	v_pk_mul_f32 v[6:7], v[6:7], v[44:45] op_sel_hi:[1,0]
	v_pk_mul_f32 v[4:5], v[4:5], v[44:45] op_sel_hi:[1,0]
	v_pk_mul_f32 v[2:3], v[2:3], v[44:45] op_sel_hi:[1,0]
	v_pk_mul_f32 v[0:1], v[0:1], v[44:45] op_sel_hi:[1,0]
	v_fmac_f32_e32 v108, v177, v44
	v_cvt_pk_bf16_f32 v40, v130, v131
	v_add_u32_e32 v130, 0x3000, v140
	v_cvt_pk_bf16_f32 v43, v54, v55
	ds_read2_b64 v[44:47], v130 offset0:128 offset1:130
	ds_read2_b64 v[54:57], v130 offset0:132 offset1:134
	v_cvt_pk_bf16_f32 v41, v132, v133
	v_cvt_pk_bf16_f32 v42, v136, v137
	v_add_u32_e32 v131, 0x4000, v140
	s_waitcnt lgkmcnt(1)
	v_mfma_f32_32x32x16_bf16 v[16:31], v[44:47], v[40:43], v[16:31]
	ds_read2_b64 v[44:47], v131 offset0:160 offset1:162
	s_waitcnt lgkmcnt(0)
	v_mfma_f32_32x32x16_bf16 v[0:15], v[44:47], v[40:43], v[0:15]
	ds_read2_b64 v[44:47], v131 offset0:164 offset1:166
	v_cvt_pk_bf16_f32 v40, v138, v139
	v_cvt_pk_bf16_f32 v41, v58, v59
	v_cvt_pk_bf16_f32 v42, v60, v61
	v_cvt_pk_bf16_f32 v43, v62, v63
	s_nop 1
	v_mfma_f32_32x32x16_bf16 v[16:31], v[54:57], v[40:43], v[16:31]
	s_waitcnt lgkmcnt(0)
	v_mfma_f32_32x32x16_bf16 v[0:15], v[44:47], v[40:43], v[0:15]
	v_cvt_pk_bf16_f32 v41, v48, v49
	v_cvt_pk_bf16_f32 v42, v50, v51
	ds_read2_b64 v[44:47], v130 offset0:136 offset1:138
	ds_read2_b64 v[48:51], v130 offset0:140 offset1:142
	v_cvt_pk_bf16_f32 v40, v32, v33
	v_cvt_pk_bf16_f32 v43, v52, v53
	v_cvt_pk_bf16_f32 v32, v34, v35
	v_cvt_pk_bf16_f32 v33, v36, v37
	s_waitcnt lgkmcnt(1)
	v_mfma_f32_32x32x16_bf16 v[16:31], v[44:47], v[40:43], v[16:31]
	ds_read2_b64 v[44:47], v131 offset0:168 offset1:170
	v_cvt_pk_bf16_f32 v34, v38, v39
	ds_read2_b64 v[36:39], v131 offset0:172 offset1:174
	v_cvt_pk_bf16_f32 v35, v134, v135
	s_waitcnt lgkmcnt(1)
	v_mfma_f32_32x32x16_bf16 v[0:15], v[44:47], v[40:43], v[0:15]
	v_mfma_f32_32x32x16_bf16 v[16:31], v[48:51], v[32:35], v[16:31]
	s_waitcnt lgkmcnt(0)
	v_mfma_f32_32x32x16_bf16 v[0:15], v[36:39], v[32:35], v[0:15]
	v_add3_u32 v32, s6, v123, v125
	s_waitcnt vmcnt(4)
	ds_write_b128 v32, v[64:67]
	v_add3_u32 v32, s6, v129, v166
	s_waitcnt vmcnt(3)
	ds_write_b128 v32, v[76:79]
	v_add3_u32 v32, s6, v167, v168
	s_waitcnt vmcnt(2)
	ds_write_b128 v32, v[96:99]
	v_add_u32_e32 v32, s6, v169
	v_add3_u32 v32, v32, v124, s63
	s_waitcnt vmcnt(1)
	ds_write2_b64 v32, v[100:101], v[102:103] offset1:1
	v_add_u32_e32 v32, s6, v170
	v_add3_u32 v32, v32, v124, s63
	s_waitcnt vmcnt(0)
	ds_write2_b64 v32, v[104:105], v[106:107] offset1:1
	s_waitcnt lgkmcnt(0)
	s_barrier
	ds_read_b128 v[32:35], v173
	ds_read_b128 v[64:67], v173 offset:32
	s_waitcnt lgkmcnt(1)
	v_mfma_f32_32x32x16_bf16 v[48:63], v[32:35], v[68:71], 0
	ds_read_b128 v[32:35], v173 offset:6656
	s_waitcnt lgkmcnt(1)
	v_mfma_f32_32x32x16_bf16 v[48:63], v[64:67], v[72:75], v[48:63]
	ds_read_b128 v[64:67], v173 offset:6688
	s_waitcnt lgkmcnt(1)
	v_mfma_f32_32x32x16_bf16 v[32:47], v[32:35], v[68:71], 0
	s_waitcnt lgkmcnt(0)
	v_mfma_f32_32x32x16_bf16 v[32:47], v[64:67], v[72:75], v[32:47]
	ds_read_b128 v[64:67], v173 offset:64
	s_waitcnt lgkmcnt(0)
	v_mfma_f32_32x32x16_bf16 v[48:63], v[64:67], v[84:87], v[48:63]
	ds_read_b128 v[64:67], v173 offset:6720
	s_waitcnt lgkmcnt(0)
	v_mfma_f32_32x32x16_bf16 v[32:47], v[64:67], v[84:87], v[32:47]
	ds_read_b128 v[64:67], v173 offset:96
	s_waitcnt lgkmcnt(0)
	v_mfma_f32_32x32x16_bf16 v[48:63], v[64:67], v[80:83], v[48:63]
	ds_read_b128 v[64:67], v173 offset:6752
	s_waitcnt lgkmcnt(0)
	v_mfma_f32_32x32x16_bf16 v[32:47], v[64:67], v[80:83], v[32:47]
	ds_read_b128 v[64:67], v173 offset:128
	s_waitcnt lgkmcnt(0)
	v_mfma_f32_32x32x16_bf16 v[48:63], v[64:67], v[92:95], v[48:63]
	ds_read_b128 v[64:67], v173 offset:6784
	s_waitcnt lgkmcnt(0)
	v_mfma_f32_32x32x16_bf16 v[32:47], v[64:67], v[92:95], v[32:47]
	ds_read_b128 v[64:67], v173 offset:160
	s_waitcnt lgkmcnt(0)
	v_mfma_f32_32x32x16_bf16 v[48:63], v[64:67], v[88:91], v[48:63]
	ds_read_b128 v[64:67], v173 offset:6816
	s_waitcnt lgkmcnt(0)
	v_mfma_f32_32x32x16_bf16 v[32:47], v[64:67], v[88:91], v[32:47]
	s_nop 11
	v_max_f32_e32 v64, v32, v32
	v_max_f32_e32 v65, v48, v48
	v_max_f32_e32 v64, v65, v64
	v_max_f32_e32 v65, v33, v33
	v_max_f32_e32 v66, v49, v49
	v_max_f32_e32 v65, v66, v65
	v_max3_f32 v64, v128, v64, v65
	v_max_f32_e32 v65, v34, v34
	v_max_f32_e32 v66, v50, v50
	v_max_f32_e32 v65, v66, v65
	v_max_f32_e32 v66, v35, v35
	v_max_f32_e32 v67, v51, v51
	v_max_f32_e32 v66, v67, v66
	v_max3_f32 v64, v64, v65, v66
	v_max_f32_e32 v65, v36, v36
	v_max_f32_e32 v66, v52, v52
	v_max_f32_e32 v65, v66, v65
	v_max_f32_e32 v66, v37, v37
	v_max_f32_e32 v67, v53, v53
	v_max_f32_e32 v66, v67, v66
	v_max3_f32 v64, v64, v65, v66
	v_max_f32_e32 v65, v38, v38
	v_max_f32_e32 v66, v54, v54
	v_max_f32_e32 v65, v66, v65
	v_max_f32_e32 v66, v39, v39
	v_max_f32_e32 v67, v55, v55
	v_max_f32_e32 v66, v67, v66
	v_max3_f32 v64, v64, v65, v66
	v_max_f32_e32 v65, v40, v40
	v_max_f32_e32 v66, v56, v56
	v_max_f32_e32 v65, v66, v65
	v_max_f32_e32 v66, v41, v41
	v_max_f32_e32 v67, v57, v57
	v_max_f32_e32 v66, v67, v66
	v_max3_f32 v64, v64, v65, v66
	v_max_f32_e32 v65, v42, v42
	v_max_f32_e32 v66, v58, v58
	v_max_f32_e32 v65, v66, v65
	v_max_f32_e32 v66, v43, v43
	v_max_f32_e32 v67, v59, v59
	v_max_f32_e32 v66, v67, v66
	v_max3_f32 v64, v64, v65, v66
	v_max_f32_e32 v65, v44, v44
	v_max_f32_e32 v66, v60, v60
	v_max_f32_e32 v65, v66, v65
	v_max_f32_e32 v66, v45, v45
	v_max_f32_e32 v67, v61, v61
	v_max_f32_e32 v66, v67, v66
	v_max3_f32 v64, v64, v65, v66
	v_max_f32_e32 v65, v46, v46
	v_max_f32_e32 v66, v62, v62
	v_max_f32_e32 v65, v66, v65
	v_max_f32_e32 v66, v47, v47
	v_max_f32_e32 v67, v63, v63
	v_max_f32_e32 v66, v67, v66
	v_max3_f32 v64, v64, v65, v66
	ds_bpermute_b32 v65, v171, v64
	s_waitcnt lgkmcnt(0)
	v_max_f32_e32 v65, v65, v65
	v_max_f32_e32 v64, v64, v65
	v_pk_add_f32 v[48:49], v[48:49], v[64:65] op_sel_hi:[1,0] neg_lo:[0,1] neg_hi:[0,1]
	v_pk_add_f32 v[32:33], v[32:33], v[64:65] op_sel_hi:[1,0] neg_lo:[0,1] neg_hi:[0,1]
	v_exp_f32_e32 v66, v48
	v_exp_f32_e32 v67, v49
	v_exp_f32_e32 v32, v32
	v_exp_f32_e32 v33, v33
	v_pk_add_f32 v[48:49], v[50:51], v[64:65] op_sel_hi:[1,0] neg_lo:[0,1] neg_hi:[0,1]
	v_pk_add_f32 v[34:35], v[34:35], v[64:65] op_sel_hi:[1,0] neg_lo:[0,1] neg_hi:[0,1]
	v_sub_f32_e32 v65, v128, v64
	v_exp_f32_e32 v68, v48
	v_exp_f32_e32 v69, v49
	v_exp_f32_e32 v48, v34
	v_exp_f32_e32 v49, v35
	v_pk_add_f32 v[50:51], v[52:53], v[64:65] op_sel_hi:[1,0] neg_lo:[0,1] neg_hi:[0,1]
	v_pk_add_f32 v[36:37], v[36:37], v[64:65] op_sel_hi:[1,0] neg_lo:[0,1] neg_hi:[0,1]
	v_exp_f32_e32 v52, v50
	v_exp_f32_e32 v53, v51
	v_exp_f32_e32 v50, v36
	v_exp_f32_e32 v51, v37
	v_pk_add_f32 v[34:35], v[32:33], v[66:67]
	v_pk_add_f32 v[36:37], v[54:55], v[64:65] op_sel_hi:[1,0] neg_lo:[0,1] neg_hi:[0,1]
	v_pk_add_f32 v[38:39], v[38:39], v[64:65] op_sel_hi:[1,0] neg_lo:[0,1] neg_hi:[0,1]
	v_pk_add_f32 v[34:35], v[34:35], 0 op_sel_hi:[1,0]
	v_pk_add_f32 v[70:71], v[48:49], v[68:69]
	v_exp_f32_e32 v54, v36
	v_exp_f32_e32 v55, v37
	v_exp_f32_e32 v72, v38
	v_exp_f32_e32 v73, v39
	v_pk_add_f32 v[34:35], v[70:71], v[34:35]
	v_pk_add_f32 v[36:37], v[50:51], v[52:53]
	v_pk_add_f32 v[44:45], v[44:45], v[64:65] op_sel_hi:[1,0] neg_lo:[0,1] neg_hi:[0,1]
	v_pk_add_f32 v[38:39], v[36:37], v[34:35]
	v_pk_add_f32 v[34:35], v[56:57], v[64:65] op_sel_hi:[1,0] neg_lo:[0,1] neg_hi:[0,1]
	v_pk_add_f32 v[36:37], v[40:41], v[64:65] op_sel_hi:[1,0] neg_lo:[0,1] neg_hi:[0,1]
	v_exp_f32_e32 v56, v34
	v_exp_f32_e32 v57, v35
	v_exp_f32_e32 v34, v36
	v_exp_f32_e32 v35, v37
	v_pk_add_f32 v[36:37], v[58:59], v[64:65] op_sel_hi:[1,0] neg_lo:[0,1] neg_hi:[0,1]
	v_pk_add_f32 v[40:41], v[42:43], v[64:65] op_sel_hi:[1,0] neg_lo:[0,1] neg_hi:[0,1]
	v_pk_add_f32 v[70:71], v[72:73], v[54:55]
	v_exp_f32_e32 v58, v36
	v_exp_f32_e32 v59, v37
	v_exp_f32_e32 v36, v40
	v_exp_f32_e32 v37, v41
	v_pk_add_f32 v[42:43], v[60:61], v[64:65] op_sel_hi:[1,0] neg_lo:[0,1] neg_hi:[0,1]
	v_pk_add_f32 v[38:39], v[70:71], v[38:39]
	v_exp_f32_e32 v60, v42
	v_exp_f32_e32 v61, v43
	v_exp_f32_e32 v70, v44
	v_exp_f32_e32 v71, v45
	v_pk_add_f32 v[42:43], v[62:63], v[64:65] op_sel_hi:[1,0] neg_lo:[0,1] neg_hi:[0,1]
	v_pk_add_f32 v[44:45], v[46:47], v[64:65] op_sel_hi:[1,0] neg_lo:[0,1] neg_hi:[0,1]
	v_exp_f32_e32 v46, v42
	v_exp_f32_e32 v47, v43
	v_exp_f32_e32 v62, v44
	v_exp_f32_e32 v63, v45
	v_pk_add_f32 v[40:41], v[34:35], v[56:57]
	v_exp_f32_e32 v64, v65
	v_pk_add_f32 v[38:39], v[40:41], v[38:39]
	v_pk_add_f32 v[40:41], v[36:37], v[58:59]
	s_nop 0
	v_pk_add_f32 v[38:39], v[40:41], v[38:39]
	v_pk_add_f32 v[40:41], v[70:71], v[60:61]
	s_nop 0
	v_pk_add_f32 v[38:39], v[40:41], v[38:39]
	v_pk_add_f32 v[40:41], v[62:63], v[46:47]
	s_nop 0
	v_pk_add_f32 v[38:39], v[40:41], v[38:39]
	s_nop 0
	v_add_f32_e32 v65, v38, v39
	ds_bpermute_b32 v74, v171, v65
	v_pk_mul_f32 v[30:31], v[30:31], v[64:65] op_sel_hi:[1,0]
	v_pk_mul_f32 v[28:29], v[28:29], v[64:65] op_sel_hi:[1,0]
	v_pk_mul_f32 v[26:27], v[26:27], v[64:65] op_sel_hi:[1,0]
	v_pk_mul_f32 v[24:25], v[24:25], v[64:65] op_sel_hi:[1,0]
	v_pk_mul_f32 v[22:23], v[22:23], v[64:65] op_sel_hi:[1,0]
	v_pk_mul_f32 v[20:21], v[20:21], v[64:65] op_sel_hi:[1,0]
	v_pk_mul_f32 v[18:19], v[18:19], v[64:65] op_sel_hi:[1,0]
	v_pk_mul_f32 v[16:17], v[16:17], v[64:65] op_sel_hi:[1,0]
	v_pk_mul_f32 v[14:15], v[14:15], v[64:65] op_sel_hi:[1,0]
	v_pk_mul_f32 v[12:13], v[12:13], v[64:65] op_sel_hi:[1,0]
	v_pk_mul_f32 v[10:11], v[10:11], v[64:65] op_sel_hi:[1,0]
	v_pk_mul_f32 v[8:9], v[8:9], v[64:65] op_sel_hi:[1,0]
	v_pk_mul_f32 v[6:7], v[6:7], v[64:65] op_sel_hi:[1,0]
	v_pk_mul_f32 v[4:5], v[4:5], v[64:65] op_sel_hi:[1,0]
	v_pk_mul_f32 v[2:3], v[2:3], v[64:65] op_sel_hi:[1,0]
	v_pk_mul_f32 v[0:1], v[0:1], v[64:65] op_sel_hi:[1,0]
	v_cvt_pk_bf16_f32 v40, v52, v53
	v_cvt_pk_bf16_f32 v41, v54, v55
	ds_read2_b64 v[42:45], v174 offset0:128 offset1:130
	ds_read2_b64 v[52:55], v174 offset0:132 offset1:134
	v_cvt_pk_bf16_f32 v38, v66, v67
	v_cvt_pk_bf16_f32 v39, v68, v69
	s_waitcnt lgkmcnt(1)
	s_nop 0
	v_mfma_f32_32x32x16_bf16 v[16:31], v[42:45], v[38:41], v[16:31]
	ds_read2_b64 v[42:45], v172 offset0:160 offset1:162
	s_waitcnt lgkmcnt(0)
	v_mfma_f32_32x32x16_bf16 v[0:15], v[42:45], v[38:41], v[0:15]
	ds_read2_b64 v[42:45], v172 offset0:164 offset1:166
	v_cvt_pk_bf16_f32 v38, v56, v57
	v_cvt_pk_bf16_f32 v39, v58, v59
	v_cvt_pk_bf16_f32 v40, v60, v61
	v_cvt_pk_bf16_f32 v41, v46, v47
	s_nop 1
	v_mfma_f32_32x32x16_bf16 v[16:31], v[52:55], v[38:41], v[16:31]
	s_waitcnt lgkmcnt(0)
	v_mfma_f32_32x32x16_bf16 v[0:15], v[42:45], v[38:41], v[0:15]
	v_cvt_pk_bf16_f32 v39, v48, v49
	ds_read2_b64 v[42:45], v174 offset0:136 offset1:138
	ds_read2_b64 v[46:49], v174 offset0:140 offset1:142
	v_cvt_pk_bf16_f32 v38, v32, v33
	v_cvt_pk_bf16_f32 v40, v50, v51
	v_cvt_pk_bf16_f32 v41, v72, v73
	v_cvt_pk_bf16_f32 v33, v36, v37
	v_cvt_pk_bf16_f32 v32, v34, v35
	s_waitcnt lgkmcnt(1)
	v_mfma_f32_32x32x16_bf16 v[16:31], v[42:45], v[38:41], v[16:31]
	ds_read2_b64 v[42:45], v172 offset0:168 offset1:170
	v_cvt_pk_bf16_f32 v34, v70, v71
	v_cvt_pk_bf16_f32 v35, v62, v63
	s_waitcnt lgkmcnt(0)
	v_mfma_f32_32x32x16_bf16 v[0:15], v[42:45], v[38:41], v[0:15]
	ds_read2_b64 v[36:39], v172 offset0:172 offset1:174
	v_mfma_f32_32x32x16_bf16 v[16:31], v[46:49], v[32:35], v[16:31]
	s_waitcnt lgkmcnt(0)
	v_mfma_f32_32x32x16_bf16 v[0:15], v[36:39], v[32:35], v[0:15]
	v_add_f32_e32 v32, v65, v74
	v_fmac_f32_e32 v32, v108, v64
	v_div_scale_f32 v33, s[0:1], v32, v32, 1.0
	v_rcp_f32_e32 v34, v33
	v_mov_b32_e32 v123, v109
	s_barrier
	v_fma_f32 v35, -v33, v34, 1.0
	v_fmac_f32_e32 v34, v35, v34
	v_div_scale_f32 v35, vcc, 1.0, v32, 1.0
	v_mul_f32_e32 v36, v35, v34
	v_fma_f32 v37, -v33, v36, v35
	v_fmac_f32_e32 v36, v37, v34
	v_fma_f32 v33, -v33, v36, v35
	v_div_fmas_f32 v33, v33, v34, v36
	v_div_fixup_f32 v32, v33, v32, 1.0
	v_pk_mul_f32 v[0:1], v[32:33], v[0:1] op_sel_hi:[0,1]
	v_pk_mul_f32 v[2:3], v[32:33], v[2:3] op_sel_hi:[0,1]
	v_lshl_add_u64 v[34:35], v[126:127], 0, v[122:123]
	v_cvt_pk_bf16_f32 v0, v0, v1
	v_cvt_pk_bf16_f32 v1, v2, v3
	global_store_dwordx2 v[34:35], v[0:1], off offset:64
	v_pk_mul_f32 v[0:1], v[32:33], v[20:21] op_sel_hi:[0,1]
	v_pk_mul_f32 v[2:3], v[32:33], v[22:23] op_sel_hi:[0,1]
	v_cvt_pk_bf16_f32 v0, v0, v1
	v_cvt_pk_bf16_f32 v1, v2, v3
	global_store_dwordx2 v[34:35], v[0:1], off offset:16
	v_pk_mul_f32 v[0:1], v[32:33], v[4:5] op_sel_hi:[0,1]
	v_pk_mul_f32 v[2:3], v[32:33], v[6:7] op_sel_hi:[0,1]
	v_cvt_pk_bf16_f32 v0, v0, v1
	v_cvt_pk_bf16_f32 v1, v2, v3
	global_store_dwordx2 v[34:35], v[0:1], off offset:80
	v_pk_mul_f32 v[0:1], v[32:33], v[24:25] op_sel_hi:[0,1]
	v_pk_mul_f32 v[2:3], v[32:33], v[26:27] op_sel_hi:[0,1]
	v_cvt_pk_bf16_f32 v0, v0, v1
	v_cvt_pk_bf16_f32 v1, v2, v3
	global_store_dwordx2 v[34:35], v[0:1], off offset:32
	v_pk_mul_f32 v[0:1], v[32:33], v[8:9] op_sel_hi:[0,1]
	v_pk_mul_f32 v[2:3], v[32:33], v[10:11] op_sel_hi:[0,1]
	v_cvt_pk_bf16_f32 v0, v0, v1
	v_cvt_pk_bf16_f32 v1, v2, v3
	global_store_dwordx2 v[34:35], v[0:1], off offset:96
	v_pk_mul_f32 v[0:1], v[32:33], v[28:29] op_sel_hi:[0,1]
	v_pk_mul_f32 v[2:3], v[32:33], v[30:31] op_sel_hi:[0,1]
	v_cvt_pk_bf16_f32 v0, v0, v1
	v_cvt_pk_bf16_f32 v1, v2, v3
	v_pk_mul_f32 v[16:17], v[32:33], v[16:17] op_sel_hi:[0,1]
	v_pk_mul_f32 v[18:19], v[32:33], v[18:19] op_sel_hi:[0,1]
	global_store_dwordx2 v[34:35], v[0:1], off offset:48
	v_pk_mul_f32 v[0:1], v[32:33], v[12:13] op_sel_hi:[0,1]
	v_pk_mul_f32 v[2:3], v[32:33], v[14:15] op_sel_hi:[0,1]
	v_cvt_pk_bf16_f32 v16, v16, v17
	v_cvt_pk_bf16_f32 v17, v18, v19
	v_cvt_pk_bf16_f32 v0, v0, v1
	v_cvt_pk_bf16_f32 v1, v2, v3
	global_store_dwordx2 v[34:35], v[16:17], off
	global_store_dwordx2 v[34:35], v[0:1], off offset:112
	s_cbranch_execnz .LBB0_643
	s_branch .LBB0_712

.LBB0_1039:
	s_add_i32 s10, s29, s85
	s_cmpk_gt_i32 s10, 0x2cff
	s_cbranch_scc1 .LBB0_1038
	s_ashr_i32 s0, s10, 6
	s_mul_hi_i32 s11, s0, 0x66666667
	s_lshr_b32 s16, s11, 31
	s_ashr_i32 s11, s11, 1
	s_add_i32 s11, s11, s16
	s_mul_i32 s16, s11, 5
	s_sub_i32 s0, s0, s16
	s_lshl_b32 s20, s0, 3
	s_and_b32 s0, s10, 7
	s_lshl_b32 s10, s10, 4
	s_lshl_b32 s11, s11, 10
	s_and_b32 s10, s10, 0x380
	s_or_b32 s10, s11, s10
	s_ashr_i32 s11, s10, 31
	s_or_b32 s16, s20, s0
	s_lshl_b64 s[18:19], s[10:11], 11
	s_add_u32 s18, s1, s18
	s_addc_u32 s19, s24, s19
	s_ashr_i32 s17, s16, 31
	v_mov_b32_e32 v4, v111
	s_lshl_b64 s[22:23], s[16:17], 18
	s_add_u32 s22, s25, s22
	v_ashrrev_i32_e32 v0, 3, v4
	v_lshrrev_b32_e32 v6, 4, v4
	v_xor_b32_e32 v8, v6, v4
	v_ashrrev_i32_e32 v1, 31, v0
	s_addc_u32 s23, s26, s23
	v_lshlrev_b64 v[0:1], 11, v[0:1]
	v_lshlrev_b32_e32 v8, 4, v8
	v_lshl_add_u64 v[2:3], s[18:19], 0, v[0:1]
	v_and_b32_e32 v108, 0x70, v8
	v_lshl_add_u64 v[0:1], s[22:23], 0, v[0:1]
	s_waitcnt vmcnt(11)
	v_lshlrev_b32_e32 v83, 4, v4
	v_lshl_add_u64 v[66:67], v[0:1], 0, v[108:109]
	v_readfirstlane_b32 s11, v83
	v_add_u32_e32 v0, 0x1000, v83
	v_lshl_add_u64 v[64:65], v[2:3], 0, v[108:109]
	s_mov_b32 m0, s11
	s_mov_b64 s[18:19], 0x10000
	v_readfirstlane_b32 s11, v0
	v_add_u32_e32 v0, 0x2000, v83
	global_load_lds_dwordx4 v[64:65], off
	v_lshl_add_u64 v[68:69], v[64:65], 0, s[18:19]
	s_mov_b32 m0, s11
	s_mov_b64 s[22:23], 0x20000
	v_readfirstlane_b32 s11, v0
	v_add_u32_e32 v0, 0x3000, v83
	global_load_lds_dwordx4 v[68:69], off
	v_lshl_add_u64 v[70:71], v[64:65], 0, s[22:23]
	s_mov_b32 m0, s11
	s_mov_b64 s[30:31], 0x30000
	v_readfirstlane_b32 s11, v0
	v_add_u32_e32 v0, 0x4000, v83
	global_load_lds_dwordx4 v[70:71], off
	v_lshl_add_u64 v[72:73], v[64:65], 0, s[30:31]
	s_mov_b32 m0, s11
	v_readfirstlane_b32 s11, v0
	v_add_u32_e32 v0, 0x5000, v83
	global_load_lds_dwordx4 v[72:73], off
	s_mov_b32 m0, s11
	v_readfirstlane_b32 s11, v0
	v_add_u32_e32 v0, 0x6000, v83
	global_load_lds_dwordx4 v[66:67], off
	v_lshl_add_u64 v[74:75], v[66:67], 0, s[18:19]
	s_mov_b32 m0, s11
	v_readfirstlane_b32 s11, v0
	v_add_u32_e32 v0, 0x7000, v83
	global_load_lds_dwordx4 v[74:75], off
	v_lshl_add_u64 v[76:77], v[66:67], 0, s[22:23]
	s_mov_b32 m0, s11
	v_readfirstlane_b32 s11, v0
	global_load_lds_dwordx4 v[76:77], off
	v_lshl_add_u64 v[78:79], v[66:67], 0, s[30:31]
	s_mov_b32 m0, s11
	v_and_b32_e32 v5, 15, v4
	global_load_lds_dwordx4 v[78:79], off
	v_lshrrev_b32_e32 v0, 1, v4
	v_and_or_b32 v0, v0, s84, v5
	v_lshlrev_b32_e32 v80, 7, v0
	v_lshlrev_b32_e32 v0, 7, v4
	v_bfe_u32 v7, v4, 4, 2
	v_and_b32_e32 v81, 0x2780, v0
	v_bfe_u32 v0, v4, 1, 3
	v_bitop3_b32 v1, v6, v0, 3 bitop3:0x6c
	v_bitop3_b32 v0, v7, v0, 4 bitop3:0x36
	v_lshlrev_b32_e32 v82, 4, v0
	v_mov_b32_e32 v0, 0
	s_waitcnt vmcnt(0)
	v_lshlrev_b32_e32 v84, 4, v1
	s_mov_b32 s17, 0
	s_mov_b32 s11, 0x8000
	v_mov_b32_e32 v1, v0
	v_mov_b32_e32 v2, v0
	v_mov_b32_e32 v3, v0
	v_mov_b32_e32 v4, v0
	v_mov_b32_e32 v5, v0
	v_mov_b32_e32 v6, v0
	v_mov_b32_e32 v7, v0
	v_mov_b32_e32 v8, v0
	v_mov_b32_e32 v9, v0
	v_mov_b32_e32 v10, v0
	v_mov_b32_e32 v11, v0
	v_mov_b32_e32 v12, v0
	v_mov_b32_e32 v13, v0
	v_mov_b32_e32 v14, v0
	v_mov_b32_e32 v15, v0
	v_mov_b32_e32 v16, v0
	v_mov_b32_e32 v17, v0
	v_mov_b32_e32 v18, v0
	v_mov_b32_e32 v19, v0
	v_mov_b32_e32 v20, v0
	v_mov_b32_e32 v21, v0
	v_mov_b32_e32 v22, v0
	v_mov_b32_e32 v23, v0
	v_mov_b32_e32 v24, v0
	v_mov_b32_e32 v25, v0
	v_mov_b32_e32 v26, v0
	v_mov_b32_e32 v27, v0
	v_mov_b32_e32 v28, v0
	v_mov_b32_e32 v29, v0
	v_mov_b32_e32 v30, v0
	v_mov_b32_e32 v31, v0
	v_mov_b32_e32 v32, v0
	v_mov_b32_e32 v33, v0
	v_mov_b32_e32 v34, v0
	v_mov_b32_e32 v35, v0
	v_mov_b32_e32 v36, v0
	v_mov_b32_e32 v37, v0
	v_mov_b32_e32 v38, v0
	v_mov_b32_e32 v39, v0
	v_mov_b32_e32 v40, v0
	v_mov_b32_e32 v41, v0
	v_mov_b32_e32 v42, v0
	v_mov_b32_e32 v43, v0
	v_mov_b32_e32 v44, v0
	v_mov_b32_e32 v45, v0
	v_mov_b32_e32 v46, v0
	v_mov_b32_e32 v47, v0
	v_mov_b32_e32 v48, v0
	v_mov_b32_e32 v49, v0
	v_mov_b32_e32 v50, v0
	v_mov_b32_e32 v51, v0
	v_mov_b32_e32 v52, v0
	v_mov_b32_e32 v53, v0
	v_mov_b32_e32 v54, v0
	v_mov_b32_e32 v55, v0
	v_mov_b32_e32 v56, v0
	v_mov_b32_e32 v57, v0
	v_mov_b32_e32 v58, v0
	v_mov_b32_e32 v59, v0
	v_mov_b32_e32 v60, v0
	v_mov_b32_e32 v61, v0
	v_mov_b32_e32 v62, v0
	v_mov_b32_e32 v63, v0
	s_waitcnt lgkmcnt(0)
	s_barrier
	v_readfirstlane_b32 s22, v83
	s_mov_b64 s[98:99], 0x80
	v_lshl_add_u64 v[64:65], v[64:65], 0, s[98:99]
	v_lshl_add_u64 v[68:69], v[68:69], 0, s[98:99]
	v_lshl_add_u64 v[70:71], v[70:71], 0, s[98:99]
	v_lshl_add_u64 v[72:73], v[72:73], 0, s[98:99]
	v_lshl_add_u64 v[66:67], v[66:67], 0, s[98:99]
	v_lshl_add_u64 v[74:75], v[74:75], 0, s[98:99]
	v_lshl_add_u64 v[76:77], v[76:77], 0, s[98:99]
	v_lshl_add_u64 v[78:79], v[78:79], 0, s[98:99]
.LBB0_1041:
	s_add_i32 s21, s11, 0xffff8000
	s_and_b32 s21, s21, 0x8000
	s_xor_b32 s17, s21, 0x8000
	s_add_u32 s17, s17, s22
	s_mov_b32 s18, s17
	s_mov_b32 m0, s18
	s_add_u32 s18, s17, 0x1000
	v_add_u32_e32 v85, s21, v80
	global_load_lds_dwordx4 v[64:65], off
	v_lshl_add_u64 v[64:65], v[64:65], 0, s[98:99]
	s_mov_b32 m0, s18
	s_add_u32 s18, s17, 0x2000
	v_or_b32_e32 v106, s21, v81
	global_load_lds_dwordx4 v[68:69], off
	v_lshl_add_u64 v[68:69], v[68:69], 0, s[98:99]
	s_mov_b32 m0, s18
	s_add_u32 s18, s17, 0x3000
	v_add_u32_e32 v250, v85, v84
	global_load_lds_dwordx4 v[70:71], off
	v_lshl_add_u64 v[70:71], v[70:71], 0, s[98:99]
	s_mov_b32 m0, s18
	s_add_u32 s18, s17, 0x4000
	v_add_u32_e32 v251, v106, v84
	global_load_lds_dwordx4 v[72:73], off
	v_lshl_add_u64 v[72:73], v[72:73], 0, s[98:99]
	s_mov_b32 m0, s18
	s_add_u32 s18, s17, 0x5000
	v_add_u32_e32 v252, v85, v82
	global_load_lds_dwordx4 v[66:67], off
	v_lshl_add_u64 v[66:67], v[66:67], 0, s[98:99]
	s_mov_b32 m0, s18
	s_add_u32 s18, s17, 0x6000
	v_add_u32_e32 v253, v106, v82
	global_load_lds_dwordx4 v[74:75], off
	v_lshl_add_u64 v[74:75], v[74:75], 0, s[98:99]
	s_mov_b32 m0, s18
	s_add_u32 s18, s17, 0x7000
	s_nop 0
	global_load_lds_dwordx4 v[76:77], off
	v_lshl_add_u64 v[76:77], v[76:77], 0, s[98:99]
	s_mov_b32 m0, s18
	s_add_u32 s18, s17, 0x8000
	s_nop 0
	global_load_lds_dwordx4 v[78:79], off
	v_lshl_add_u64 v[78:79], v[78:79], 0, s[98:99]
	ds_read_b128 v[86:89], v250
	ds_read_b128 v[102:105], v251 offset:16384
	ds_read_b128 v[122:125], v251 offset:18432
	ds_read_b128 v[126:129], v251 offset:20480
	ds_read_b128 v[130:133], v251 offset:22528
	ds_read_b128 v[90:93], v250 offset:2048
	ds_read_b128 v[94:97], v250 offset:4096
	ds_read_b128 v[98:101], v250 offset:6144
	ds_read_b128 v[218:221], v252
	ds_read_b128 v[234:237], v253 offset:16384
	ds_read_b128 v[238:241], v253 offset:18432
	ds_read_b128 v[242:245], v253 offset:20480
	ds_read_b128 v[246:249], v253 offset:22528
	ds_read_b128 v[222:225], v252 offset:2048
	ds_read_b128 v[226:229], v252 offset:4096
	s_waitcnt lgkmcnt(13)
	v_mfma_f32_16x16x32_bf16 v[60:63], v[102:105], v[86:89], v[60:63]
	ds_read_b128 v[230:233], v252 offset:6144
	s_waitcnt lgkmcnt(13)
	v_mfma_f32_16x16x32_bf16 v[56:59], v[122:125], v[86:89], v[56:59]
	s_waitcnt lgkmcnt(12)
	v_mfma_f32_16x16x32_bf16 v[52:55], v[126:129], v[86:89], v[52:55]
	s_waitcnt lgkmcnt(11)
	v_mfma_f32_16x16x32_bf16 v[48:51], v[130:133], v[86:89], v[48:51]
	s_waitcnt lgkmcnt(10)
	v_mfma_f32_16x16x32_bf16 v[44:47], v[102:105], v[90:93], v[44:47]
	v_mfma_f32_16x16x32_bf16 v[40:43], v[122:125], v[90:93], v[40:43]
	v_mfma_f32_16x16x32_bf16 v[36:39], v[126:129], v[90:93], v[36:39]
	v_mfma_f32_16x16x32_bf16 v[32:35], v[130:133], v[90:93], v[32:35]
	s_waitcnt lgkmcnt(9)
	v_mfma_f32_16x16x32_bf16 v[28:31], v[102:105], v[94:97], v[28:31]
	v_mfma_f32_16x16x32_bf16 v[24:27], v[122:125], v[94:97], v[24:27]
	v_mfma_f32_16x16x32_bf16 v[20:23], v[126:129], v[94:97], v[20:23]
	v_mfma_f32_16x16x32_bf16 v[16:19], v[130:133], v[94:97], v[16:19]
	s_waitcnt lgkmcnt(8)
	v_mfma_f32_16x16x32_bf16 v[12:15], v[102:105], v[98:101], v[12:15]
	v_mfma_f32_16x16x32_bf16 v[8:11], v[122:125], v[98:101], v[8:11]
	v_mfma_f32_16x16x32_bf16 v[4:7], v[126:129], v[98:101], v[4:7]
	v_mfma_f32_16x16x32_bf16 v[0:3], v[130:133], v[98:101], v[0:3]
	s_waitcnt lgkmcnt(6)
	v_mfma_f32_16x16x32_bf16 v[60:63], v[234:237], v[218:221], v[60:63]
	s_waitcnt lgkmcnt(5)
	v_mfma_f32_16x16x32_bf16 v[56:59], v[238:241], v[218:221], v[56:59]
	s_waitcnt lgkmcnt(4)
	v_mfma_f32_16x16x32_bf16 v[52:55], v[242:245], v[218:221], v[52:55]
	s_waitcnt lgkmcnt(3)
	v_mfma_f32_16x16x32_bf16 v[48:51], v[246:249], v[218:221], v[48:51]
	s_waitcnt lgkmcnt(2)
	v_mfma_f32_16x16x32_bf16 v[44:47], v[234:237], v[222:225], v[44:47]
	v_mfma_f32_16x16x32_bf16 v[40:43], v[238:241], v[222:225], v[40:43]
	v_mfma_f32_16x16x32_bf16 v[36:39], v[242:245], v[222:225], v[36:39]
	v_mfma_f32_16x16x32_bf16 v[32:35], v[246:249], v[222:225], v[32:35]
	s_waitcnt lgkmcnt(1)
	v_mfma_f32_16x16x32_bf16 v[28:31], v[234:237], v[226:229], v[28:31]
	v_mfma_f32_16x16x32_bf16 v[24:27], v[238:241], v[226:229], v[24:27]
	v_mfma_f32_16x16x32_bf16 v[20:23], v[242:245], v[226:229], v[20:23]
	v_mfma_f32_16x16x32_bf16 v[16:19], v[246:249], v[226:229], v[16:19]
	s_waitcnt lgkmcnt(0)
	v_mfma_f32_16x16x32_bf16 v[12:15], v[234:237], v[230:233], v[12:15]
	v_mfma_f32_16x16x32_bf16 v[8:11], v[238:241], v[230:233], v[8:11]
	v_mfma_f32_16x16x32_bf16 v[4:7], v[242:245], v[230:233], v[4:7]
	v_mfma_f32_16x16x32_bf16 v[0:3], v[246:249], v[230:233], v[0:3]
	s_add_i32 s11, s11, 0x8000
	s_cmp_lg_u32 s11, 0x80000
	s_waitcnt vmcnt(0)
	s_barrier
	s_cbranch_scc1 .LBB0_1041
	v_add_u32_e32 v83, v81, v84
	ds_read_b128 v[64:67], v83 offset:49152
	ds_read_b128 v[72:75], v83 offset:51200
	v_add_u32_e32 v88, v80, v84
	ds_read_b128 v[76:79], v83 offset:53248
	ds_read_b128 v[84:87], v83 offset:55296
	ds_read_b128 v[68:71], v88 offset:32768
	v_add_u32_e32 v81, v81, v82
	s_waitcnt lgkmcnt(0)
	v_mfma_f32_16x16x32_bf16 v[60:63], v[64:67], v[68:71], v[60:63]
	v_mfma_f32_16x16x32_bf16 v[56:59], v[72:75], v[68:71], v[56:59]
	v_mfma_f32_16x16x32_bf16 v[52:55], v[76:79], v[68:71], v[52:55]
	v_mfma_f32_16x16x32_bf16 v[48:51], v[84:87], v[68:71], v[48:51]
	ds_read_b128 v[68:71], v88 offset:34816
	s_waitcnt lgkmcnt(0)
	v_mfma_f32_16x16x32_bf16 v[44:47], v[64:67], v[68:71], v[44:47]
	v_mfma_f32_16x16x32_bf16 v[40:43], v[72:75], v[68:71], v[40:43]
	v_mfma_f32_16x16x32_bf16 v[36:39], v[76:79], v[68:71], v[36:39]
	v_mfma_f32_16x16x32_bf16 v[32:35], v[84:87], v[68:71], v[32:35]
	ds_read_b128 v[68:71], v88 offset:36864
	s_waitcnt lgkmcnt(0)
	v_mfma_f32_16x16x32_bf16 v[28:31], v[64:67], v[68:71], v[28:31]
	v_mfma_f32_16x16x32_bf16 v[24:27], v[72:75], v[68:71], v[24:27]
	v_mfma_f32_16x16x32_bf16 v[20:23], v[76:79], v[68:71], v[20:23]
	v_mfma_f32_16x16x32_bf16 v[16:19], v[84:87], v[68:71], v[16:19]
	ds_read_b128 v[68:71], v88 offset:38912
	s_waitcnt lgkmcnt(0)
	v_mfma_f32_16x16x32_bf16 v[0:3], v[84:87], v[68:71], v[0:3]
	v_add_u32_e32 v84, v80, v82
	v_mfma_f32_16x16x32_bf16 v[12:15], v[64:67], v[68:71], v[12:15]
	ds_read_b128 v[64:67], v81 offset:49152
	v_mfma_f32_16x16x32_bf16 v[8:11], v[72:75], v[68:71], v[8:11]
	ds_read_b128 v[72:75], v81 offset:51200
	v_mfma_f32_16x16x32_bf16 v[4:7], v[76:79], v[68:71], v[4:7]
	ds_read_b128 v[68:71], v84 offset:32768
	ds_read_b128 v[76:79], v81 offset:53248
	ds_read_b128 v[80:83], v81 offset:55296
	s_waitcnt lgkmcnt(2)
	v_mfma_f32_16x16x32_bf16 v[60:63], v[64:67], v[68:71], v[60:63]
	v_mfma_f32_16x16x32_bf16 v[56:59], v[72:75], v[68:71], v[56:59]
	s_waitcnt lgkmcnt(1)
	v_mfma_f32_16x16x32_bf16 v[52:55], v[76:79], v[68:71], v[52:55]
	s_waitcnt lgkmcnt(0)
	v_mfma_f32_16x16x32_bf16 v[48:51], v[80:83], v[68:71], v[48:51]
	ds_read_b128 v[68:71], v84 offset:34816
	s_waitcnt lgkmcnt(0)
	v_mfma_f32_16x16x32_bf16 v[44:47], v[64:67], v[68:71], v[44:47]
	v_mfma_f32_16x16x32_bf16 v[40:43], v[72:75], v[68:71], v[40:43]
	v_mfma_f32_16x16x32_bf16 v[36:39], v[76:79], v[68:71], v[36:39]
	v_mfma_f32_16x16x32_bf16 v[32:35], v[80:83], v[68:71], v[32:35]
	ds_read_b128 v[68:71], v84 offset:36864
	s_waitcnt lgkmcnt(0)
	v_mfma_f32_16x16x32_bf16 v[28:31], v[64:67], v[68:71], v[28:31]
	v_mfma_f32_16x16x32_bf16 v[24:27], v[72:75], v[68:71], v[24:27]
	v_mfma_f32_16x16x32_bf16 v[20:23], v[76:79], v[68:71], v[20:23]
	v_mfma_f32_16x16x32_bf16 v[16:19], v[80:83], v[68:71], v[16:19]
	ds_read_b128 v[68:71], v84 offset:38912
	s_waitcnt lgkmcnt(0)
	v_mfma_f32_16x16x32_bf16 v[12:15], v[64:67], v[68:71], v[12:15]
	v_mfma_f32_16x16x32_bf16 v[8:11], v[72:75], v[68:71], v[8:11]
	v_mfma_f32_16x16x32_bf16 v[4:7], v[76:79], v[68:71], v[4:7]
	v_mfma_f32_16x16x32_bf16 v[0:3], v[80:83], v[68:71], v[0:3]
	v_mov_b32_e32 v64, v111
	s_barrier
	s_cmp_gt_i32 s16, 15
	v_ashrrev_i32_e32 v68, 7, v64
	v_bfe_u32 v70, v64, 6, 1
	v_and_b32_e32 v71, 15, v64
	v_bfe_u32 v69, v64, 4, 2
	s_mov_b64 s[18:19], -1
	s_cbranch_scc0 .LBB0_1046
	s_add_i32 s20, s20, -16
	s_cmp_eq_u32 s20, 0
	s_mov_b64 s[18:19], s[2:3]
	s_cbranch_scc1 .LBB0_1045
	s_lshr_b32 s11, s20, 3
	s_add_i32 s11, s11, -1
	s_mul_hi_u32 s17, s11, 0x4800000
	s_mul_i32 s11, s11, 0x4800000
	s_add_u32 s18, s27, s11
	s_addc_u32 s19, s28, s17

.LBB0_1147:
	s_add_i32 s2, s23, s85
	s_cmpk_gt_i32 s2, 0x8ff
	s_cbranch_scc1 .LBB0_1146
	s_lshl_b32 s10, s2, 4
	s_and_b32 s0, s2, 7
	s_and_b32 s2, s10, 0xffffff80
	s_ashr_i32 s3, s2, 31
	s_lshl_b64 s[16:17], s[2:3], 11
	s_add_u32 s16, s1, s16
	v_mov_b32_e32 v4, v111
	s_addc_u32 s17, s18, s17
	s_lshl_b32 s3, s0, 18
	s_add_u32 s24, s19, s3
	v_ashrrev_i32_e32 v0, 3, v4
	v_lshrrev_b32_e32 v6, 4, v4
	v_xor_b32_e32 v8, v6, v4
	v_ashrrev_i32_e32 v1, 31, v0
	s_addc_u32 s25, s20, 0
	v_lshlrev_b64 v[0:1], 11, v[0:1]
	v_lshlrev_b32_e32 v8, 4, v8
	v_lshl_add_u64 v[2:3], s[16:17], 0, v[0:1]
	v_and_b32_e32 v108, 0x70, v8
	v_lshl_add_u64 v[0:1], s[24:25], 0, v[0:1]
	s_waitcnt vmcnt(11)
	v_lshlrev_b32_e32 v83, 4, v4
	v_lshl_add_u64 v[66:67], v[0:1], 0, v[108:109]
	v_readfirstlane_b32 s3, v83
	v_add_u32_e32 v0, 0x1000, v83
	v_lshl_add_u64 v[64:65], v[2:3], 0, v[108:109]
	s_mov_b32 m0, s3
	s_mov_b64 s[16:17], 0x10000
	v_readfirstlane_b32 s3, v0
	v_add_u32_e32 v0, 0x2000, v83
	global_load_lds_dwordx4 v[64:65], off
	v_lshl_add_u64 v[68:69], v[64:65], 0, s[16:17]
	s_mov_b32 m0, s3
	s_mov_b64 s[24:25], 0x20000
	v_readfirstlane_b32 s3, v0
	v_add_u32_e32 v0, 0x3000, v83
	global_load_lds_dwordx4 v[68:69], off
	v_lshl_add_u64 v[70:71], v[64:65], 0, s[24:25]
	s_mov_b32 m0, s3
	s_mov_b64 s[26:27], 0x30000
	v_readfirstlane_b32 s3, v0
	v_add_u32_e32 v0, 0x4000, v83
	global_load_lds_dwordx4 v[70:71], off
	v_lshl_add_u64 v[72:73], v[64:65], 0, s[26:27]
	s_mov_b32 m0, s3
	v_readfirstlane_b32 s3, v0
	v_add_u32_e32 v0, 0x5000, v83
	global_load_lds_dwordx4 v[72:73], off
	s_mov_b32 m0, s3
	v_readfirstlane_b32 s3, v0
	v_add_u32_e32 v0, 0x6000, v83
	global_load_lds_dwordx4 v[66:67], off
	v_lshl_add_u64 v[74:75], v[66:67], 0, s[16:17]
	s_mov_b32 m0, s3
	v_readfirstlane_b32 s3, v0
	v_add_u32_e32 v0, 0x7000, v83
	global_load_lds_dwordx4 v[74:75], off
	v_lshl_add_u64 v[76:77], v[66:67], 0, s[24:25]
	s_mov_b32 m0, s3
	v_readfirstlane_b32 s3, v0
	global_load_lds_dwordx4 v[76:77], off
	v_lshl_add_u64 v[78:79], v[66:67], 0, s[26:27]
	s_mov_b32 m0, s3
	v_and_b32_e32 v5, 15, v4
	global_load_lds_dwordx4 v[78:79], off
	v_lshrrev_b32_e32 v0, 1, v4
	v_and_or_b32 v0, v0, s84, v5
	v_lshlrev_b32_e32 v80, 7, v0
	v_lshlrev_b32_e32 v0, 7, v4
	v_bfe_u32 v7, v4, 4, 2
	v_and_b32_e32 v81, 0x2780, v0
	v_bfe_u32 v0, v4, 1, 3
	v_bitop3_b32 v1, v6, v0, 3 bitop3:0x6c
	v_bitop3_b32 v0, v7, v0, 4 bitop3:0x36
	v_lshlrev_b32_e32 v82, 4, v0
	v_mov_b32_e32 v0, 0
	s_waitcnt vmcnt(0)
	v_lshlrev_b32_e32 v84, 4, v1
	s_mov_b32 s11, 0
	s_mov_b32 s3, 0x8000
	v_mov_b32_e32 v1, v0
	v_mov_b32_e32 v2, v0
	v_mov_b32_e32 v3, v0
	v_mov_b32_e32 v4, v0
	v_mov_b32_e32 v5, v0
	v_mov_b32_e32 v6, v0
	v_mov_b32_e32 v7, v0
	v_mov_b32_e32 v8, v0
	v_mov_b32_e32 v9, v0
	v_mov_b32_e32 v10, v0
	v_mov_b32_e32 v11, v0
	v_mov_b32_e32 v12, v0
	v_mov_b32_e32 v13, v0
	v_mov_b32_e32 v14, v0
	v_mov_b32_e32 v15, v0
	v_mov_b32_e32 v16, v0
	v_mov_b32_e32 v17, v0
	v_mov_b32_e32 v18, v0
	v_mov_b32_e32 v19, v0
	v_mov_b32_e32 v20, v0
	v_mov_b32_e32 v21, v0
	v_mov_b32_e32 v22, v0
	v_mov_b32_e32 v23, v0
	v_mov_b32_e32 v24, v0
	v_mov_b32_e32 v25, v0
	v_mov_b32_e32 v26, v0
	v_mov_b32_e32 v27, v0
	v_mov_b32_e32 v28, v0
	v_mov_b32_e32 v29, v0
	v_mov_b32_e32 v30, v0
	v_mov_b32_e32 v31, v0
	v_mov_b32_e32 v32, v0
	v_mov_b32_e32 v33, v0
	v_mov_b32_e32 v34, v0
	v_mov_b32_e32 v35, v0
	v_mov_b32_e32 v36, v0
	v_mov_b32_e32 v37, v0
	v_mov_b32_e32 v38, v0
	v_mov_b32_e32 v39, v0
	v_mov_b32_e32 v40, v0
	v_mov_b32_e32 v41, v0
	v_mov_b32_e32 v42, v0
	v_mov_b32_e32 v43, v0
	v_mov_b32_e32 v44, v0
	v_mov_b32_e32 v45, v0
	v_mov_b32_e32 v46, v0
	v_mov_b32_e32 v47, v0
	v_mov_b32_e32 v48, v0
	v_mov_b32_e32 v49, v0
	v_mov_b32_e32 v50, v0
	v_mov_b32_e32 v51, v0
	v_mov_b32_e32 v52, v0
	v_mov_b32_e32 v53, v0
	v_mov_b32_e32 v54, v0
	v_mov_b32_e32 v55, v0
	v_mov_b32_e32 v56, v0
	v_mov_b32_e32 v57, v0
	v_mov_b32_e32 v58, v0
	v_mov_b32_e32 v59, v0
	v_mov_b32_e32 v60, v0
	v_mov_b32_e32 v61, v0
	v_mov_b32_e32 v62, v0
	v_mov_b32_e32 v63, v0
	s_waitcnt lgkmcnt(0)
	s_barrier
	v_readfirstlane_b32 s25, v83
	s_mov_b64 s[98:99], 0x80
	v_lshl_add_u64 v[64:65], v[64:65], 0, s[98:99]
	v_lshl_add_u64 v[68:69], v[68:69], 0, s[98:99]
	v_lshl_add_u64 v[70:71], v[70:71], 0, s[98:99]
	v_lshl_add_u64 v[72:73], v[72:73], 0, s[98:99]
	v_lshl_add_u64 v[66:67], v[66:67], 0, s[98:99]
	v_lshl_add_u64 v[74:75], v[74:75], 0, s[98:99]
	v_lshl_add_u64 v[76:77], v[76:77], 0, s[98:99]
	v_lshl_add_u64 v[78:79], v[78:79], 0, s[98:99]
.LBB0_1149:
	s_add_i32 s24, s3, 0xffff8000
	s_and_b32 s24, s24, 0x8000
	s_xor_b32 s11, s24, 0x8000
	s_add_u32 s11, s11, s25
	s_mov_b32 s16, s11
	s_mov_b32 m0, s16
	s_add_u32 s16, s11, 0x1000
	v_add_u32_e32 v85, s24, v80
	global_load_lds_dwordx4 v[64:65], off
	v_lshl_add_u64 v[64:65], v[64:65], 0, s[98:99]
	s_mov_b32 m0, s16
	s_add_u32 s16, s11, 0x2000
	v_or_b32_e32 v106, s24, v81
	global_load_lds_dwordx4 v[68:69], off
	v_lshl_add_u64 v[68:69], v[68:69], 0, s[98:99]
	s_mov_b32 m0, s16
	s_add_u32 s16, s11, 0x3000
	v_add_u32_e32 v250, v85, v84
	global_load_lds_dwordx4 v[70:71], off
	v_lshl_add_u64 v[70:71], v[70:71], 0, s[98:99]
	s_mov_b32 m0, s16
	s_add_u32 s16, s11, 0x4000
	v_add_u32_e32 v251, v106, v84
	global_load_lds_dwordx4 v[72:73], off
	v_lshl_add_u64 v[72:73], v[72:73], 0, s[98:99]
	s_mov_b32 m0, s16
	s_add_u32 s16, s11, 0x5000
	v_add_u32_e32 v252, v85, v82
	global_load_lds_dwordx4 v[66:67], off
	v_lshl_add_u64 v[66:67], v[66:67], 0, s[98:99]
	s_mov_b32 m0, s16
	s_add_u32 s16, s11, 0x6000
	v_add_u32_e32 v253, v106, v82
	global_load_lds_dwordx4 v[74:75], off
	v_lshl_add_u64 v[74:75], v[74:75], 0, s[98:99]
	s_mov_b32 m0, s16
	s_add_u32 s16, s11, 0x7000
	s_nop 0
	global_load_lds_dwordx4 v[76:77], off
	v_lshl_add_u64 v[76:77], v[76:77], 0, s[98:99]
	s_mov_b32 m0, s16
	s_add_u32 s16, s11, 0x8000
	s_nop 0
	global_load_lds_dwordx4 v[78:79], off
	v_lshl_add_u64 v[78:79], v[78:79], 0, s[98:99]
	ds_read_b128 v[86:89], v250
	ds_read_b128 v[102:105], v251 offset:16384
	ds_read_b128 v[122:125], v251 offset:18432
	ds_read_b128 v[126:129], v251 offset:20480
	ds_read_b128 v[130:133], v251 offset:22528
	ds_read_b128 v[90:93], v250 offset:2048
	ds_read_b128 v[94:97], v250 offset:4096
	ds_read_b128 v[98:101], v250 offset:6144
	ds_read_b128 v[218:221], v252
	ds_read_b128 v[234:237], v253 offset:16384
	ds_read_b128 v[238:241], v253 offset:18432
	ds_read_b128 v[242:245], v253 offset:20480
	ds_read_b128 v[246:249], v253 offset:22528
	ds_read_b128 v[222:225], v252 offset:2048
	ds_read_b128 v[226:229], v252 offset:4096
	s_waitcnt lgkmcnt(13)
	v_mfma_f32_16x16x32_bf16 v[60:63], v[102:105], v[86:89], v[60:63]
	ds_read_b128 v[230:233], v252 offset:6144
	s_waitcnt lgkmcnt(13)
	v_mfma_f32_16x16x32_bf16 v[56:59], v[122:125], v[86:89], v[56:59]
	s_waitcnt lgkmcnt(12)
	v_mfma_f32_16x16x32_bf16 v[52:55], v[126:129], v[86:89], v[52:55]
	s_waitcnt lgkmcnt(11)
	v_mfma_f32_16x16x32_bf16 v[48:51], v[130:133], v[86:89], v[48:51]
	s_waitcnt lgkmcnt(10)
	v_mfma_f32_16x16x32_bf16 v[44:47], v[102:105], v[90:93], v[44:47]
	v_mfma_f32_16x16x32_bf16 v[40:43], v[122:125], v[90:93], v[40:43]
	v_mfma_f32_16x16x32_bf16 v[36:39], v[126:129], v[90:93], v[36:39]
	v_mfma_f32_16x16x32_bf16 v[32:35], v[130:133], v[90:93], v[32:35]
	s_waitcnt lgkmcnt(9)
	v_mfma_f32_16x16x32_bf16 v[28:31], v[102:105], v[94:97], v[28:31]
	v_mfma_f32_16x16x32_bf16 v[24:27], v[122:125], v[94:97], v[24:27]
	v_mfma_f32_16x16x32_bf16 v[20:23], v[126:129], v[94:97], v[20:23]
	v_mfma_f32_16x16x32_bf16 v[16:19], v[130:133], v[94:97], v[16:19]
	s_waitcnt lgkmcnt(8)
	v_mfma_f32_16x16x32_bf16 v[12:15], v[102:105], v[98:101], v[12:15]
	v_mfma_f32_16x16x32_bf16 v[8:11], v[122:125], v[98:101], v[8:11]
	v_mfma_f32_16x16x32_bf16 v[4:7], v[126:129], v[98:101], v[4:7]
	v_mfma_f32_16x16x32_bf16 v[0:3], v[130:133], v[98:101], v[0:3]
	s_waitcnt lgkmcnt(6)
	v_mfma_f32_16x16x32_bf16 v[60:63], v[234:237], v[218:221], v[60:63]
	s_waitcnt lgkmcnt(5)
	v_mfma_f32_16x16x32_bf16 v[56:59], v[238:241], v[218:221], v[56:59]
	s_waitcnt lgkmcnt(4)
	v_mfma_f32_16x16x32_bf16 v[52:55], v[242:245], v[218:221], v[52:55]
	s_waitcnt lgkmcnt(3)
	v_mfma_f32_16x16x32_bf16 v[48:51], v[246:249], v[218:221], v[48:51]
	s_waitcnt lgkmcnt(2)
	v_mfma_f32_16x16x32_bf16 v[44:47], v[234:237], v[222:225], v[44:47]
	v_mfma_f32_16x16x32_bf16 v[40:43], v[238:241], v[222:225], v[40:43]
	v_mfma_f32_16x16x32_bf16 v[36:39], v[242:245], v[222:225], v[36:39]
	v_mfma_f32_16x16x32_bf16 v[32:35], v[246:249], v[222:225], v[32:35]
	s_waitcnt lgkmcnt(1)
	v_mfma_f32_16x16x32_bf16 v[28:31], v[234:237], v[226:229], v[28:31]
	v_mfma_f32_16x16x32_bf16 v[24:27], v[238:241], v[226:229], v[24:27]
	v_mfma_f32_16x16x32_bf16 v[20:23], v[242:245], v[226:229], v[20:23]
	v_mfma_f32_16x16x32_bf16 v[16:19], v[246:249], v[226:229], v[16:19]
	s_waitcnt lgkmcnt(0)
	v_mfma_f32_16x16x32_bf16 v[12:15], v[234:237], v[230:233], v[12:15]
	v_mfma_f32_16x16x32_bf16 v[8:11], v[238:241], v[230:233], v[8:11]
	v_mfma_f32_16x16x32_bf16 v[4:7], v[242:245], v[230:233], v[4:7]
	v_mfma_f32_16x16x32_bf16 v[0:3], v[246:249], v[230:233], v[0:3]
	s_add_i32 s3, s3, 0x8000
	s_cmp_lg_u32 s3, 0x80000
	s_waitcnt vmcnt(0)
	s_barrier
	s_cbranch_scc1 .LBB0_1149
	v_add_u32_e32 v83, v81, v84
	ds_read_b128 v[64:67], v83 offset:49152
	ds_read_b128 v[72:75], v83 offset:51200
	v_add_u32_e32 v96, v80, v84
	ds_read_b128 v[76:79], v83 offset:53248
	ds_read_b128 v[84:87], v83 offset:55296
	ds_read_b128 v[68:71], v96 offset:32768
	v_add_u32_e32 v104, v80, v82
	s_addk_i32 s10, 0xf000
	s_ashr_i32 s3, s10, 12
	s_waitcnt lgkmcnt(0)
	v_mfma_f32_16x16x32_bf16 v[60:63], v[64:67], v[68:71], v[60:63]
	v_mfma_f32_16x16x32_bf16 v[56:59], v[72:75], v[68:71], v[56:59]
	v_mfma_f32_16x16x32_bf16 v[52:55], v[76:79], v[68:71], v[52:55]
	v_mfma_f32_16x16x32_bf16 v[48:51], v[84:87], v[68:71], v[48:51]
	ds_read_b128 v[68:71], v96 offset:34816
	s_waitcnt lgkmcnt(0)
	v_mfma_f32_16x16x32_bf16 v[88:91], v[64:67], v[68:71], v[44:47]
	s_nop 2
	ds_read_b128 v[44:47], v96 offset:36864
	s_waitcnt lgkmcnt(0)
	v_mfma_f32_16x16x32_bf16 v[92:95], v[72:75], v[44:47], v[24:27]
	s_nop 2
	ds_read_b128 v[24:27], v96 offset:38912
	v_mfma_f32_16x16x32_bf16 v[40:43], v[72:75], v[68:71], v[40:43]
	s_waitcnt lgkmcnt(0)
	v_mfma_f32_16x16x32_bf16 v[72:75], v[72:75], v[24:27], v[8:11]
	s_nop 2
	v_add_u32_e32 v8, v81, v82
	v_mfma_f32_16x16x32_bf16 v[36:39], v[76:79], v[68:71], v[36:39]
	ds_read_b128 v[100:103], v8 offset:49152
	ds_read_b128 v[80:83], v8 offset:51200
	v_mfma_f32_16x16x32_bf16 v[32:35], v[84:87], v[68:71], v[32:35]
	v_mfma_f32_16x16x32_bf16 v[20:23], v[76:79], v[44:47], v[20:23]
	v_mfma_f32_16x16x32_bf16 v[16:19], v[84:87], v[44:47], v[16:19]
	v_mfma_f32_16x16x32_bf16 v[76:79], v[76:79], v[24:27], v[4:7]
	v_mfma_f32_16x16x32_bf16 v[0:3], v[84:87], v[24:27], v[0:3]
	s_nop 1
	ds_read_b128 v[4:7], v104 offset:32768
	ds_read_b128 v[84:87], v8 offset:53248
	v_mfma_f32_16x16x32_bf16 v[68:71], v[64:67], v[44:47], v[28:31]
	s_waitcnt lgkmcnt(0)
	v_mfma_f32_16x16x32_bf16 v[28:31], v[84:87], v[4:7], v[52:55]
	s_nop 2
	ds_read_b128 v[52:55], v8 offset:55296
	v_mfma_f32_16x16x32_bf16 v[96:99], v[64:67], v[24:27], v[12:15]
	v_mfma_f32_16x16x32_bf16 v[64:67], v[100:103], v[4:7], v[60:63]
	v_mfma_f32_16x16x32_bf16 v[44:47], v[80:83], v[4:7], v[56:59]
	s_waitcnt lgkmcnt(0)
	v_mfma_f32_16x16x32_bf16 v[12:15], v[52:55], v[4:7], v[48:51]
	ds_read_b128 v[4:7], v104 offset:34816
	s_waitcnt lgkmcnt(0)
	v_mfma_f32_16x16x32_bf16 v[60:63], v[100:103], v[4:7], v[88:91]
	v_mfma_f32_16x16x32_bf16 v[40:43], v[80:83], v[4:7], v[40:43]
	v_mfma_f32_16x16x32_bf16 v[24:27], v[84:87], v[4:7], v[36:39]
	v_mfma_f32_16x16x32_bf16 v[8:11], v[52:55], v[4:7], v[32:35]
	ds_read_b128 v[4:7], v104 offset:36864
	s_waitcnt lgkmcnt(0)
	v_mfma_f32_16x16x32_bf16 v[56:59], v[100:103], v[4:7], v[68:71]
	s_nop 2
	ds_read_b128 v[68:71], v104 offset:38912
	v_mfma_f32_16x16x32_bf16 v[36:39], v[80:83], v[4:7], v[92:95]
	v_mfma_f32_16x16x32_bf16 v[20:23], v[84:87], v[4:7], v[20:23]
	v_mfma_f32_16x16x32_bf16 v[4:7], v[52:55], v[4:7], v[16:19]
	s_waitcnt lgkmcnt(0)
	v_mfma_f32_16x16x32_bf16 v[48:51], v[100:103], v[68:71], v[96:99]
	v_mfma_f32_16x16x32_bf16 v[32:35], v[80:83], v[68:71], v[72:75]
	v_mfma_f32_16x16x32_bf16 v[16:19], v[84:87], v[68:71], v[76:79]
	v_mfma_f32_16x16x32_bf16 v[0:3], v[52:55], v[68:71], v[0:3]
	s_lshl_b32 s0, s0, 7
	s_mulk_i32 s3, 0xc00
	s_cmpk_gt_i32 s2, 0xfff
	v_mov_b32_e32 v52, v111
	s_cselect_b32 s10, s3, 0x6000
	s_barrier
	s_ashr_i32 s11, s10, 31
	v_lshrrev_b32_e32 v54, 2, v52
	v_and_b32_e32 v53, 64, v52
	v_and_b32_e32 v54, 12, v54
	s_lshl_b64 s[10:11], s[10:11], 2
	v_or3_b32 v53, v53, s0, v54
	s_add_u32 s0, s21, s10
	s_addc_u32 s3, s22, s11
	v_ashrrev_i32_e32 v54, 1, v52
	s_add_u32 s10, s0, 0x1792000
	v_and_b32_e32 v54, 0xffffffc0, v54
	s_addc_u32 s11, s3, 0
	v_add_u32_e32 v54, s2, v54
	v_lshlrev_b32_e32 v108, 2, v53
	v_and_or_b32 v68, v52, 15, v54
	global_load_dwordx4 v[52:55], v108, s[10:11]
	s_mov_b64 s[2:3], -1
	s_and_b64 vcc, exec, s[8:9]
	s_cbranch_vccz .LBB0_1152
	v_ashrrev_i32_e32 v69, 31, v68
	s_mov_b64 s[2:3], 0
